# restores the wait state between P3 pass-1 x4 stores and the VALU write of their data registers (hazard padding)
# speedup vs baseline: 1.0016x; 1.0016x over previous
.LBB0_556:
	s_lshl_b32 s13, s60, 8
	v_mov_b32_e32 v144, v151
	v_mov_b32_e32 v145, v150
	s_add_i32 s13, s13, s69
	s_andn2_b64 vcc, exec, s[4:5]
	v_add_u32_e32 v146, s13, v145
	s_lshl_b32 s13, s77, 8
	s_or_b32 s13, s13, s72
	v_lshl_add_u32 v144, v144, 3, s13
	v_ashrrev_i32_e32 v145, 31, v144
	v_lshlrev_b64 v[144:145], 1, v[144:145]
	v_ashrrev_i32_e32 v147, 31, v146
	v_lshl_add_u64 v[148:149], s[56:57], 0, v[144:145]
	v_lshlrev_b64 v[156:157], 12, v[146:147]
	v_lshl_add_u64 v[160:161], v[148:149], 0, v[156:157]
	v_add_u32_e32 v172, 16, v146
	global_load_dwordx4 v[156:159], v[160:161], off
	s_nop 0
	global_load_dwordx4 v[160:163], v[160:161], off offset:256
	v_ashrrev_i32_e32 v173, 31, v172
	v_lshlrev_b64 v[164:165], 12, v[172:173]
	v_lshl_add_u64 v[168:169], v[148:149], 0, v[164:165]
	global_load_dwordx4 v[164:167], v[168:169], off
	v_add_u32_e32 v188, 32, v146
	global_load_dwordx4 v[168:171], v[168:169], off offset:256
	v_add_u32_e32 v190, 48, v146
	v_ashrrev_i32_e32 v189, 31, v188
	v_ashrrev_i32_e32 v191, 31, v190
	v_lshlrev_b64 v[174:175], 11, v[146:147]
	v_lshlrev_b64 v[176:177], 12, v[188:189]
	v_lshlrev_b64 v[178:179], 12, v[190:191]
	v_lshl_add_u64 v[174:175], s[42:43], 0, v[174:175]
	v_lshlrev_b64 v[172:173], 11, v[172:173]
	v_lshl_add_u64 v[176:177], v[148:149], 0, v[176:177]
	v_lshl_add_u64 v[184:185], v[148:149], 0, v[178:179]
	v_lshl_add_u64 v[192:193], v[174:175], 0, v[144:145]
	v_lshl_add_u64 v[194:195], s[42:43], 0, v[172:173]
	global_load_dwordx4 v[172:175], v[176:177], off
	s_nop 0
	global_load_dwordx4 v[176:179], v[176:177], off offset:256
	s_nop 0
	global_load_dwordx4 v[180:183], v[184:185], off
	s_nop 0
	global_load_dwordx4 v[184:187], v[184:185], off offset:256
	v_lshl_add_u64 v[194:195], v[194:195], 0, v[144:145]
	s_mov_b64 s[4:5], -1
	v_add_u32_e32 v250, 0x80, v146
	v_ashrrev_i32_e32 v251, 31, v250
	v_lshlrev_b64 v[252:253], 12, v[250:251]
	v_lshl_add_u64 v[250:251], v[148:149], 0, v[252:253]
	global_load_dwordx4 v[206:209], v[250:251], off
	global_load_dwordx4 v[210:213], v[250:251], off offset:256
	v_add_u32_e32 v250, 0x90, v146
	v_ashrrev_i32_e32 v251, 31, v250
	v_lshlrev_b64 v[252:253], 12, v[250:251]
	v_lshl_add_u64 v[250:251], v[148:149], 0, v[252:253]
	global_load_dwordx4 v[214:217], v[250:251], off
	global_load_dwordx4 v[218:221], v[250:251], off offset:256
	v_add_u32_e32 v250, 0xa0, v146
	v_ashrrev_i32_e32 v251, 31, v250
	v_lshlrev_b64 v[252:253], 12, v[250:251]
	v_lshl_add_u64 v[250:251], v[148:149], 0, v[252:253]
	global_load_dwordx4 v[222:225], v[250:251], off
	global_load_dwordx4 v[226:229], v[250:251], off offset:256
	v_add_u32_e32 v250, 0xb0, v146
	v_ashrrev_i32_e32 v251, 31, v250
	v_lshlrev_b64 v[252:253], 12, v[250:251]
	v_lshl_add_u64 v[250:251], v[148:149], 0, v[252:253]
	global_load_dwordx4 v[230:233], v[250:251], off
	global_load_dwordx4 v[234:237], v[250:251], off offset:256
	s_waitcnt vmcnt(8)
	v_lshlrev_b32_e32 v147, 16, v156
	v_and_b32_e32 v156, 0xffff0000, v156
	v_lshlrev_b32_e32 v201, 16, v162
	v_lshlrev_b32_e32 v196, 16, v157
	v_and_b32_e32 v157, 0xffff0000, v157
	v_lshlrev_b32_e32 v197, 16, v158
	v_and_b32_e32 v158, 0xffff0000, v158
	v_lshlrev_b32_e32 v198, 16, v159
	v_and_b32_e32 v159, 0xffff0000, v159
	v_lshlrev_b32_e32 v199, 16, v160
	v_and_b32_e32 v160, 0xffff0000, v160
	v_and_b32_e32 v162, 0xffff0000, v162
	v_lshlrev_b32_e32 v202, 16, v163
	v_and_b32_e32 v163, 0xffff0000, v163
	v_mul_f32_e32 v124, v124, v147
	v_mul_f32_e32 v125, v125, v156
	v_mul_f32_e32 v147, v104, v201
	v_cvt_pk_bf16_f32 v104, v124, v125
	v_lshlrev_b32_e32 v200, 16, v161
	v_and_b32_e32 v161, 0xffff0000, v161
	v_mul_f32_e32 v126, v126, v196
	v_mul_f32_e32 v127, v127, v157
	v_mul_f32_e32 v120, v120, v197
	v_mul_f32_e32 v121, v121, v158
	v_mul_f32_e32 v122, v122, v198
	v_mul_f32_e32 v123, v123, v159
	v_mul_f32_e32 v112, v112, v199
	v_mul_f32_e32 v113, v113, v160
	v_mul_f32_e32 v156, v105, v162
	v_mul_f32_e32 v157, v106, v202
	v_mul_f32_e32 v158, v107, v163
	v_cvt_pk_bf16_f32 v105, v126, v127
	v_cvt_pk_bf16_f32 v106, v120, v121
	v_cvt_pk_bf16_f32 v107, v122, v123
	global_store_dwordx4 v[192:193], v[104:107], off
	v_mul_f32_e32 v114, v114, v200
	v_mul_f32_e32 v115, v115, v161
	v_cvt_pk_bf16_f32 v104, v112, v113
	v_cvt_pk_bf16_f32 v105, v114, v115
	v_cvt_pk_bf16_f32 v106, v147, v156
	v_cvt_pk_bf16_f32 v107, v157, v158
	global_store_dwordx4 v[192:193], v[104:107], off offset:256
	v_lshlrev_b32_e32 v205, 16, v166
	v_lshlrev_b32_e32 v203, 16, v164
	v_and_b32_e32 v104, 0xffff0000, v166
	v_mul_f32_e32 v107, v109, v104
	v_lshlrev_b32_e32 v104, 16, v167
	v_and_b32_e32 v164, 0xffff0000, v164
	v_mul_f32_e32 v106, v108, v205
	v_mul_f32_e32 v108, v110, v104
	v_and_b32_e32 v104, 0xffff0000, v167
	v_lshlrev_b32_e32 v204, 16, v165
	v_and_b32_e32 v165, 0xffff0000, v165
	v_mul_f32_e32 v116, v116, v203
	v_mul_f32_e32 v117, v117, v164
	v_mul_f32_e32 v109, v111, v104
	v_cvt_pk_bf16_f32 v104, v116, v117
	v_mul_f32_e32 v118, v118, v204
	v_mul_f32_e32 v119, v119, v165
	v_cvt_pk_bf16_f32 v105, v118, v119
	v_cvt_pk_bf16_f32 v106, v106, v107
	v_cvt_pk_bf16_f32 v107, v108, v109
	global_store_dwordx4 v[194:195], v[104:107], off
	s_nop 1
	v_lshlrev_b32_e32 v104, 16, v168
	v_mul_f32_e32 v100, v100, v104
	v_and_b32_e32 v104, 0xffff0000, v168
	v_mul_f32_e32 v101, v101, v104
	v_lshlrev_b32_e32 v104, 16, v169
	v_mul_f32_e32 v102, v102, v104
	v_and_b32_e32 v104, 0xffff0000, v169
	v_mul_f32_e32 v103, v103, v104
	v_lshlrev_b32_e32 v104, 16, v170
	v_mul_f32_e32 v104, v92, v104
	v_and_b32_e32 v92, 0xffff0000, v170
	v_mul_f32_e32 v105, v93, v92
	v_lshlrev_b32_e32 v92, 16, v171
	v_mul_f32_e32 v106, v94, v92
	v_and_b32_e32 v92, 0xffff0000, v171
	v_mul_f32_e32 v95, v95, v92
	v_cvt_pk_bf16_f32 v92, v100, v101
	v_cvt_pk_bf16_f32 v93, v102, v103
	v_cvt_pk_bf16_f32 v94, v104, v105
	v_cvt_pk_bf16_f32 v95, v106, v95
	global_store_dwordx4 v[194:195], v[92:95], off offset:256
	v_add_u32_e32 v102, 0xb0, v146
	v_ashrrev_i32_e32 v103, 31, v102
	v_lshlrev_b32_e32 v94, 16, v172
	v_mul_f32_e32 v94, v96, v94
	v_lshlrev_b32_e32 v96, 16, v173
	v_and_b32_e32 v95, 0xffff0000, v172
	v_mul_f32_e32 v96, v98, v96
	v_lshlrev_b32_e32 v98, 16, v174
	v_mul_f32_e32 v95, v97, v95
	v_and_b32_e32 v97, 0xffff0000, v173
	v_mul_f32_e32 v98, v88, v98
	v_and_b32_e32 v88, 0xffff0000, v174
	v_lshlrev_b64 v[92:93], 11, v[188:189]
	v_mul_f32_e32 v97, v99, v97
	v_mul_f32_e32 v99, v89, v88
	v_lshlrev_b32_e32 v88, 16, v175
	v_lshl_add_u64 v[92:93], s[42:43], 0, v[92:93]
	v_mul_f32_e32 v100, v90, v88
	v_and_b32_e32 v88, 0xffff0000, v175
	v_lshl_add_u64 v[92:93], v[92:93], 0, v[144:145]
	v_mul_f32_e32 v91, v91, v88
	v_cvt_pk_bf16_f32 v88, v94, v95
	v_cvt_pk_bf16_f32 v89, v96, v97
	v_cvt_pk_bf16_f32 v90, v98, v99
	v_cvt_pk_bf16_f32 v91, v100, v91
	global_store_dwordx4 v[92:93], v[88:91], off
	v_add_u32_e32 v96, 0x80, v146
	v_ashrrev_i32_e32 v97, 31, v96
	v_lshlrev_b32_e32 v88, 16, v176
	v_mul_f32_e32 v84, v84, v88
	v_and_b32_e32 v88, 0xffff0000, v176
	v_mul_f32_e32 v85, v85, v88
	v_lshlrev_b32_e32 v88, 16, v177
	v_mul_f32_e32 v86, v86, v88
	v_and_b32_e32 v88, 0xffff0000, v177
	v_mul_f32_e32 v87, v87, v88
	v_lshlrev_b32_e32 v88, 16, v178
	v_mul_f32_e32 v88, v76, v88
	v_and_b32_e32 v76, 0xffff0000, v178
	v_mul_f32_e32 v89, v77, v76
	v_lshlrev_b32_e32 v76, 16, v179
	v_mul_f32_e32 v90, v78, v76
	v_and_b32_e32 v76, 0xffff0000, v179
	v_mul_f32_e32 v79, v79, v76
	v_cvt_pk_bf16_f32 v76, v84, v85
	v_cvt_pk_bf16_f32 v77, v86, v87
	v_cvt_pk_bf16_f32 v78, v88, v89
	v_cvt_pk_bf16_f32 v79, v90, v79
	global_store_dwordx4 v[92:93], v[76:79], off offset:256
	v_add_u32_e32 v98, 0x90, v146
	v_ashrrev_i32_e32 v99, 31, v98
	v_lshlrev_b32_e32 v78, 16, v180
	v_mul_f32_e32 v78, v80, v78
	v_lshlrev_b32_e32 v80, 16, v181
	v_and_b32_e32 v79, 0xffff0000, v180
	v_mul_f32_e32 v80, v82, v80
	v_lshlrev_b32_e32 v82, 16, v182
	v_mul_f32_e32 v79, v81, v79
	v_and_b32_e32 v81, 0xffff0000, v181
	v_mul_f32_e32 v82, v72, v82
	v_and_b32_e32 v72, 0xffff0000, v182
	v_lshlrev_b64 v[76:77], 11, v[190:191]
	v_mul_f32_e32 v81, v83, v81
	v_mul_f32_e32 v83, v73, v72
	v_lshlrev_b32_e32 v72, 16, v183
	v_lshl_add_u64 v[76:77], s[42:43], 0, v[76:77]
	v_mul_f32_e32 v84, v74, v72
	v_and_b32_e32 v72, 0xffff0000, v183
	v_lshl_add_u64 v[76:77], v[76:77], 0, v[144:145]
	v_mul_f32_e32 v75, v75, v72
	v_cvt_pk_bf16_f32 v72, v78, v79
	v_cvt_pk_bf16_f32 v73, v80, v81
	v_cvt_pk_bf16_f32 v74, v82, v83
	v_cvt_pk_bf16_f32 v75, v84, v75
	global_store_dwordx4 v[76:77], v[72:75], off
	v_add_u32_e32 v100, 0xa0, v146
	v_ashrrev_i32_e32 v101, 31, v100
	v_lshlrev_b32_e32 v72, 16, v184
	v_mul_f32_e32 v68, v68, v72
	v_and_b32_e32 v72, 0xffff0000, v184
	v_mul_f32_e32 v69, v69, v72
	v_lshlrev_b32_e32 v72, 16, v185
	v_mul_f32_e32 v70, v70, v72
	v_and_b32_e32 v72, 0xffff0000, v185
	v_mul_f32_e32 v71, v71, v72
	v_lshlrev_b32_e32 v72, 16, v186
	v_mul_f32_e32 v72, v64, v72
	v_and_b32_e32 v64, 0xffff0000, v186
	v_mul_f32_e32 v73, v65, v64
	v_lshlrev_b32_e32 v64, 16, v187
	v_mul_f32_e32 v74, v66, v64
	v_and_b32_e32 v64, 0xffff0000, v187
	v_mul_f32_e32 v67, v67, v64
	v_cvt_pk_bf16_f32 v64, v68, v69
	v_cvt_pk_bf16_f32 v65, v70, v71
	v_cvt_pk_bf16_f32 v66, v72, v73
	v_cvt_pk_bf16_f32 v67, v74, v67
	global_store_dwordx4 v[76:77], v[64:67], off offset:256
	v_lshlrev_b64 v[72:73], 12, v[98:99]
	v_lshl_add_u64 v[76:77], v[148:149], 0, v[72:73]
	v_lshlrev_b64 v[64:65], 12, v[96:97]
	v_lshl_add_u64 v[68:69], v[148:149], 0, v[64:65]
	s_waitcnt vmcnt(8)
	v_mov_b32_e32 v64, v206
	v_mov_b32_e32 v65, v207
	v_mov_b32_e32 v66, v208
	v_mov_b32_e32 v67, v209
	s_nop 0
	v_mov_b32_e32 v68, v210
	v_mov_b32_e32 v69, v211
	v_mov_b32_e32 v70, v212
	v_mov_b32_e32 v71, v213
	s_nop 0
	v_mov_b32_e32 v72, v214
	v_mov_b32_e32 v73, v215
	v_mov_b32_e32 v74, v216
	v_mov_b32_e32 v75, v217
	s_nop 0
	v_mov_b32_e32 v76, v218
	v_mov_b32_e32 v77, v219
	v_mov_b32_e32 v78, v220
	v_mov_b32_e32 v79, v221
	v_lshlrev_b64 v[80:81], 12, v[100:101]
	v_lshl_add_u64 v[84:85], v[148:149], 0, v[80:81]
	v_mov_b32_e32 v80, v222
	v_mov_b32_e32 v81, v223
	v_mov_b32_e32 v82, v224
	v_mov_b32_e32 v83, v225
	s_nop 0
	v_mov_b32_e32 v84, v226
	v_mov_b32_e32 v85, v227
	v_mov_b32_e32 v86, v228
	v_mov_b32_e32 v87, v229
	v_lshlrev_b64 v[88:89], 12, v[102:103]
	v_lshl_add_u64 v[92:93], v[148:149], 0, v[88:89]
	v_mov_b32_e32 v88, v230
	v_mov_b32_e32 v89, v231
	v_mov_b32_e32 v90, v232
	v_mov_b32_e32 v91, v233
	s_nop 0
	v_mov_b32_e32 v92, v234
	v_mov_b32_e32 v93, v235
	v_mov_b32_e32 v94, v236
	v_mov_b32_e32 v95, v237
	v_lshlrev_b64 v[96:97], 11, v[96:97]
	v_lshl_add_u64 v[96:97], s[42:43], 0, v[96:97]
	v_lshl_add_u64 v[96:97], v[96:97], 0, v[144:145]
	s_nop 0
	v_lshlrev_b32_e32 v104, 16, v64
	v_and_b32_e32 v64, 0xffff0000, v64
	v_mul_f32_e32 v61, v61, v64
	v_lshlrev_b32_e32 v64, 16, v65
	v_mul_f32_e32 v62, v62, v64
	v_and_b32_e32 v64, 0xffff0000, v65
	v_mul_f32_e32 v63, v63, v64
	v_lshlrev_b32_e32 v64, 16, v66
	v_mul_f32_e32 v64, v56, v64
	v_and_b32_e32 v56, 0xffff0000, v66
	v_mul_f32_e32 v65, v57, v56
	v_lshlrev_b32_e32 v56, 16, v67
	v_mul_f32_e32 v66, v58, v56
	v_and_b32_e32 v56, 0xffff0000, v67
	v_mul_f32_e32 v60, v60, v104
	v_mul_f32_e32 v59, v59, v56
	v_cvt_pk_bf16_f32 v56, v60, v61
	v_cvt_pk_bf16_f32 v57, v62, v63
	v_cvt_pk_bf16_f32 v58, v64, v65
	v_cvt_pk_bf16_f32 v59, v66, v59
	global_store_dwordx4 v[96:97], v[56:59], off
	s_nop 0
	s_nop 0
	v_lshlrev_b32_e32 v56, 16, v68
	v_mul_f32_e32 v52, v52, v56
	v_and_b32_e32 v56, 0xffff0000, v68
	v_mul_f32_e32 v53, v53, v56
	v_lshlrev_b32_e32 v56, 16, v69
	v_mul_f32_e32 v54, v54, v56
	v_and_b32_e32 v56, 0xffff0000, v69
	v_mul_f32_e32 v55, v55, v56
	v_lshlrev_b32_e32 v56, 16, v70
	v_mul_f32_e32 v56, v44, v56
	v_and_b32_e32 v44, 0xffff0000, v70
	v_mul_f32_e32 v57, v45, v44
	v_lshlrev_b32_e32 v44, 16, v71
	v_mul_f32_e32 v58, v46, v44
	v_and_b32_e32 v44, 0xffff0000, v71
	v_mul_f32_e32 v47, v47, v44
	v_cvt_pk_bf16_f32 v44, v52, v53
	v_cvt_pk_bf16_f32 v45, v54, v55
	v_cvt_pk_bf16_f32 v46, v56, v57
	v_cvt_pk_bf16_f32 v47, v58, v47
	global_store_dwordx4 v[96:97], v[44:47], off offset:256
	s_nop 0
	s_nop 0
	v_lshlrev_b32_e32 v46, 16, v72
	v_mul_f32_e32 v46, v48, v46
	v_lshlrev_b32_e32 v48, 16, v73
	v_and_b32_e32 v47, 0xffff0000, v72
	v_mul_f32_e32 v48, v50, v48
	v_lshlrev_b32_e32 v50, 16, v74
	v_mul_f32_e32 v47, v49, v47
	v_and_b32_e32 v49, 0xffff0000, v73
	v_mul_f32_e32 v50, v40, v50
	v_and_b32_e32 v40, 0xffff0000, v74
	v_lshlrev_b64 v[44:45], 11, v[98:99]
	v_mul_f32_e32 v49, v51, v49
	v_mul_f32_e32 v51, v41, v40
	v_lshlrev_b32_e32 v40, 16, v75
	v_lshl_add_u64 v[44:45], s[42:43], 0, v[44:45]
	v_mul_f32_e32 v52, v42, v40
	v_and_b32_e32 v40, 0xffff0000, v75
	v_lshl_add_u64 v[44:45], v[44:45], 0, v[144:145]
	v_mul_f32_e32 v43, v43, v40
	v_cvt_pk_bf16_f32 v40, v46, v47
	v_cvt_pk_bf16_f32 v41, v48, v49
	v_cvt_pk_bf16_f32 v42, v50, v51
	v_cvt_pk_bf16_f32 v43, v52, v43
	global_store_dwordx4 v[44:45], v[40:43], off
	s_nop 0
	s_nop 0
	v_lshlrev_b32_e32 v40, 16, v76
	v_mul_f32_e32 v36, v36, v40
	v_and_b32_e32 v40, 0xffff0000, v76
	v_mul_f32_e32 v37, v37, v40
	v_lshlrev_b32_e32 v40, 16, v77
	v_mul_f32_e32 v38, v38, v40
	v_and_b32_e32 v40, 0xffff0000, v77
	v_mul_f32_e32 v39, v39, v40
	v_lshlrev_b32_e32 v40, 16, v78
	v_mul_f32_e32 v40, v28, v40
	v_and_b32_e32 v28, 0xffff0000, v78
	v_mul_f32_e32 v41, v29, v28
	v_lshlrev_b32_e32 v28, 16, v79
	v_mul_f32_e32 v42, v30, v28
	v_and_b32_e32 v28, 0xffff0000, v79
	v_mul_f32_e32 v31, v31, v28
	v_cvt_pk_bf16_f32 v28, v36, v37
	v_cvt_pk_bf16_f32 v29, v38, v39
	v_cvt_pk_bf16_f32 v30, v40, v41
	v_cvt_pk_bf16_f32 v31, v42, v31
	global_store_dwordx4 v[44:45], v[28:31], off offset:256
	s_nop 0
	s_nop 0
	v_lshlrev_b32_e32 v30, 16, v80
	v_mul_f32_e32 v30, v32, v30
	v_lshlrev_b32_e32 v32, 16, v81
	v_and_b32_e32 v31, 0xffff0000, v80
	v_mul_f32_e32 v32, v34, v32
	v_lshlrev_b32_e32 v34, 16, v82
	v_mul_f32_e32 v31, v33, v31
	v_and_b32_e32 v33, 0xffff0000, v81
	v_mul_f32_e32 v34, v24, v34
	v_and_b32_e32 v24, 0xffff0000, v82
	v_lshlrev_b64 v[28:29], 11, v[100:101]
	v_mul_f32_e32 v33, v35, v33
	v_mul_f32_e32 v35, v25, v24
	v_lshlrev_b32_e32 v24, 16, v83
	v_lshl_add_u64 v[28:29], s[42:43], 0, v[28:29]
	v_mul_f32_e32 v36, v26, v24
	v_and_b32_e32 v24, 0xffff0000, v83
	v_lshl_add_u64 v[28:29], v[28:29], 0, v[144:145]
	v_mul_f32_e32 v27, v27, v24
	v_cvt_pk_bf16_f32 v24, v30, v31
	v_cvt_pk_bf16_f32 v25, v32, v33
	v_cvt_pk_bf16_f32 v26, v34, v35
	v_cvt_pk_bf16_f32 v27, v36, v27
	global_store_dwordx4 v[28:29], v[24:27], off
	s_nop 0
	s_nop 0
	v_lshlrev_b32_e32 v24, 16, v84
	v_mul_f32_e32 v20, v20, v24
	v_and_b32_e32 v24, 0xffff0000, v84
	v_mul_f32_e32 v21, v21, v24
	v_lshlrev_b32_e32 v24, 16, v85
	v_mul_f32_e32 v22, v22, v24
	v_and_b32_e32 v24, 0xffff0000, v85
	v_mul_f32_e32 v23, v23, v24
	v_lshlrev_b32_e32 v24, 16, v86
	v_mul_f32_e32 v24, v12, v24
	v_and_b32_e32 v12, 0xffff0000, v86
	v_mul_f32_e32 v25, v13, v12
	v_lshlrev_b32_e32 v12, 16, v87
	v_mul_f32_e32 v26, v14, v12
	v_and_b32_e32 v12, 0xffff0000, v87
	v_mul_f32_e32 v15, v15, v12
	v_cvt_pk_bf16_f32 v12, v20, v21
	v_cvt_pk_bf16_f32 v13, v22, v23
	v_cvt_pk_bf16_f32 v14, v24, v25
	v_cvt_pk_bf16_f32 v15, v26, v15
	global_store_dwordx4 v[28:29], v[12:15], off offset:256
	s_nop 0
	s_nop 0
	v_lshlrev_b32_e32 v14, 16, v88
	v_mul_f32_e32 v14, v16, v14
	v_lshlrev_b32_e32 v16, 16, v89
	v_and_b32_e32 v15, 0xffff0000, v88
	v_mul_f32_e32 v16, v18, v16
	v_lshlrev_b32_e32 v18, 16, v90
	v_mul_f32_e32 v15, v17, v15
	v_and_b32_e32 v17, 0xffff0000, v89
	v_mul_f32_e32 v18, v8, v18
	v_and_b32_e32 v8, 0xffff0000, v90
	v_lshlrev_b64 v[12:13], 11, v[102:103]
	v_mul_f32_e32 v17, v19, v17
	v_mul_f32_e32 v19, v9, v8
	v_lshlrev_b32_e32 v8, 16, v91
	v_lshl_add_u64 v[12:13], s[42:43], 0, v[12:13]
	v_mul_f32_e32 v20, v10, v8
	v_and_b32_e32 v8, 0xffff0000, v91
	v_lshl_add_u64 v[12:13], v[12:13], 0, v[144:145]
	v_mul_f32_e32 v11, v11, v8
	v_cvt_pk_bf16_f32 v8, v14, v15
	v_cvt_pk_bf16_f32 v9, v16, v17
	v_cvt_pk_bf16_f32 v10, v18, v19
	v_cvt_pk_bf16_f32 v11, v20, v11
	global_store_dwordx4 v[12:13], v[8:11], off
	s_nop 0
	s_nop 0
	v_lshlrev_b32_e32 v8, 16, v92
	v_mul_f32_e32 v4, v4, v8
	v_and_b32_e32 v8, 0xffff0000, v92
	v_mul_f32_e32 v5, v5, v8
	v_lshlrev_b32_e32 v8, 16, v93
	v_mul_f32_e32 v6, v6, v8
	v_and_b32_e32 v8, 0xffff0000, v93
	v_mul_f32_e32 v7, v7, v8
	v_lshlrev_b32_e32 v8, 16, v94
	v_mul_f32_e32 v8, v0, v8
	v_and_b32_e32 v0, 0xffff0000, v94
	v_mul_f32_e32 v9, v1, v0
	v_lshlrev_b32_e32 v0, 16, v95
	v_mul_f32_e32 v10, v2, v0
	v_and_b32_e32 v0, 0xffff0000, v95
	v_mul_f32_e32 v3, v3, v0
	v_cvt_pk_bf16_f32 v0, v4, v5
	v_cvt_pk_bf16_f32 v1, v6, v7
	v_cvt_pk_bf16_f32 v2, v8, v9
	v_cvt_pk_bf16_f32 v3, v10, v3
	global_store_dwordx4 v[12:13], v[0:3], off offset:256
	s_mov_b32 s99, 1
	s_cbranch_vccnz .LBB0_545
	s_andn2_b64 vcc, exec, s[6:7]
	s_cbranch_vccnz .LBB0_544
	s_barrier
	s_branch .LBB0_544

.LBB0_1416:
	s_lshl_b32 s11, s36, 8
	v_mov_b32_e32 v128, v179
	v_mov_b32_e32 v129, v178
	s_add_i32 s11, s11, s70
	s_andn2_b64 vcc, exec, s[8:9]
	v_add_u32_e32 v170, s11, v129
	s_lshl_b32 s11, s37, 8
	s_or_b32 s11, s11, s71
	v_lshl_add_u32 v128, v128, 3, s11
	v_ashrrev_i32_e32 v129, 31, v128
	v_lshlrev_b64 v[168:169], 1, v[128:129]
	v_ashrrev_i32_e32 v171, 31, v170
	v_lshl_add_u64 v[172:173], s[56:57], 0, v[168:169]
	v_lshlrev_b64 v[128:129], 12, v[170:171]
	v_lshl_add_u64 v[128:129], v[172:173], 0, v[128:129]
	global_load_dwordx4 v[184:187], v[128:129], off
	global_load_dwordx4 v[188:191], v[128:129], off offset:256
	v_add_u32_e32 v192, 16, v170
	v_ashrrev_i32_e32 v193, 31, v192
	v_lshlrev_b64 v[128:129], 12, v[192:193]
	v_lshl_add_u64 v[128:129], v[172:173], 0, v[128:129]
	global_load_dwordx4 v[148:151], v[128:129], off
	global_load_dwordx4 v[144:147], v[128:129], off offset:256
	v_add_u32_e32 v176, 32, v170
	v_ashrrev_i32_e32 v177, 31, v176
	v_lshlrev_b64 v[128:129], 12, v[176:177]
	v_lshl_add_u64 v[128:129], v[172:173], 0, v[128:129]
	global_load_dwordx4 v[140:143], v[128:129], off
	global_load_dwordx4 v[132:135], v[128:129], off offset:256
	v_add_u32_e32 v174, 48, v170
	v_ashrrev_i32_e32 v175, 31, v174
	v_lshlrev_b64 v[128:129], 12, v[174:175]
	v_lshl_add_u64 v[128:129], v[172:173], 0, v[128:129]
	global_load_dwordx4 v[136:139], v[128:129], off
	s_nop 0
	global_load_dwordx4 v[128:131], v[128:129], off offset:256
	v_lshlrev_b64 v[194:195], 11, v[170:171]
	v_lshl_add_u64 v[194:195], s[42:43], 0, v[194:195]
	v_lshl_add_u64 v[194:195], v[194:195], 0, v[168:169]
	s_mov_b64 s[36:37], -1
	v_add_u32_e32 v200, 0x80, v170
	v_ashrrev_i32_e32 v201, 31, v200
	v_lshlrev_b64 v[252:253], 12, v[200:201]
	v_lshl_add_u64 v[200:201], v[172:173], 0, v[252:253]
	global_load_dwordx4 v[196:199], v[200:201], off
	global_load_dwordx4 v[204:207], v[200:201], off offset:256
	v_add_u32_e32 v200, 0x90, v170
	v_ashrrev_i32_e32 v201, 31, v200
	v_lshlrev_b64 v[252:253], 12, v[200:201]
	v_lshl_add_u64 v[200:201], v[172:173], 0, v[252:253]
	global_load_dwordx4 v[208:211], v[200:201], off
	global_load_dwordx4 v[212:215], v[200:201], off offset:256
	v_add_u32_e32 v200, 0xa0, v170
	v_ashrrev_i32_e32 v201, 31, v200
	v_lshlrev_b64 v[252:253], 12, v[200:201]
	v_lshl_add_u64 v[200:201], v[172:173], 0, v[252:253]
	global_load_dwordx4 v[216:219], v[200:201], off
	global_load_dwordx4 v[220:223], v[200:201], off offset:256
	v_add_u32_e32 v200, 0xb0, v170
	v_ashrrev_i32_e32 v201, 31, v200
	v_lshlrev_b64 v[252:253], 12, v[200:201]
	v_lshl_add_u64 v[200:201], v[172:173], 0, v[252:253]
	global_load_dwordx4 v[224:227], v[200:201], off
	global_load_dwordx4 v[228:231], v[200:201], off offset:256
	s_waitcnt vmcnt(8)
	v_lshlrev_b32_e32 v171, 16, v184
	v_mul_f32_e32 v124, v124, v171
	v_and_b32_e32 v171, 0xffff0000, v184
	v_mul_f32_e32 v125, v125, v171
	v_lshlrev_b32_e32 v171, 16, v185
	v_mul_f32_e32 v126, v126, v171
	v_and_b32_e32 v171, 0xffff0000, v185
	v_mul_f32_e32 v127, v127, v171
	v_lshlrev_b32_e32 v171, 16, v186
	v_mul_f32_e32 v171, v120, v171
	v_and_b32_e32 v120, 0xffff0000, v186
	v_mul_f32_e32 v184, v121, v120
	v_lshlrev_b32_e32 v120, 16, v187
	v_mul_f32_e32 v185, v122, v120
	v_and_b32_e32 v120, 0xffff0000, v187
	v_mul_f32_e32 v123, v123, v120
	v_cvt_pk_bf16_f32 v120, v124, v125
	v_cvt_pk_bf16_f32 v121, v126, v127
	v_cvt_pk_bf16_f32 v122, v171, v184
	v_cvt_pk_bf16_f32 v123, v185, v123
	global_store_dwordx4 v[194:195], v[120:123], off
	s_nop 1
	v_lshlrev_b32_e32 v120, 16, v188
	v_mul_f32_e32 v116, v116, v120
	v_and_b32_e32 v120, 0xffff0000, v188
	v_mul_f32_e32 v117, v117, v120
	v_lshlrev_b32_e32 v120, 16, v189
	v_mul_f32_e32 v118, v118, v120
	v_and_b32_e32 v120, 0xffff0000, v189
	v_mul_f32_e32 v119, v119, v120
	v_lshlrev_b32_e32 v120, 16, v190
	v_mul_f32_e32 v120, v112, v120
	v_and_b32_e32 v112, 0xffff0000, v190
	v_mul_f32_e32 v121, v113, v112
	v_lshlrev_b32_e32 v112, 16, v191
	v_mul_f32_e32 v122, v114, v112
	v_and_b32_e32 v112, 0xffff0000, v191
	v_mul_f32_e32 v115, v115, v112
	v_cvt_pk_bf16_f32 v112, v116, v117
	v_cvt_pk_bf16_f32 v113, v118, v119
	v_cvt_pk_bf16_f32 v114, v120, v121
	v_cvt_pk_bf16_f32 v115, v122, v115
	global_store_dwordx4 v[194:195], v[112:115], off offset:256
	s_nop 1
	v_lshlrev_b32_e32 v114, 16, v148
	v_mul_f32_e32 v108, v108, v114
	v_and_b32_e32 v114, 0xffff0000, v148
	v_mul_f32_e32 v109, v109, v114
	v_lshlrev_b32_e32 v114, 16, v149
	v_mul_f32_e32 v110, v110, v114
	v_and_b32_e32 v114, 0xffff0000, v149
	v_mul_f32_e32 v111, v111, v114
	v_lshlrev_b32_e32 v114, 16, v150
	v_mul_f32_e32 v114, v104, v114
	v_and_b32_e32 v104, 0xffff0000, v150
	v_lshlrev_b64 v[112:113], 11, v[192:193]
	v_mul_f32_e32 v115, v105, v104
	v_lshlrev_b32_e32 v104, 16, v151
	v_lshl_add_u64 v[112:113], s[42:43], 0, v[112:113]
	v_mul_f32_e32 v116, v106, v104
	v_and_b32_e32 v104, 0xffff0000, v151
	v_lshl_add_u64 v[112:113], v[112:113], 0, v[168:169]
	v_mul_f32_e32 v107, v107, v104
	v_cvt_pk_bf16_f32 v104, v108, v109
	v_cvt_pk_bf16_f32 v105, v110, v111
	v_cvt_pk_bf16_f32 v106, v114, v115
	v_cvt_pk_bf16_f32 v107, v116, v107
	global_store_dwordx4 v[112:113], v[104:107], off
	s_nop 1
	v_lshlrev_b32_e32 v104, 16, v144
	v_mul_f32_e32 v100, v100, v104
	v_and_b32_e32 v104, 0xffff0000, v144
	v_mul_f32_e32 v101, v101, v104
	v_lshlrev_b32_e32 v104, 16, v145
	v_mul_f32_e32 v102, v102, v104
	v_and_b32_e32 v104, 0xffff0000, v145
	v_mul_f32_e32 v103, v103, v104
	v_lshlrev_b32_e32 v104, 16, v146
	v_mul_f32_e32 v104, v92, v104
	v_and_b32_e32 v92, 0xffff0000, v146
	v_mul_f32_e32 v105, v93, v92
	v_lshlrev_b32_e32 v92, 16, v147
	v_mul_f32_e32 v106, v94, v92
	v_and_b32_e32 v92, 0xffff0000, v147
	v_mul_f32_e32 v95, v95, v92
	v_cvt_pk_bf16_f32 v92, v100, v101
	v_cvt_pk_bf16_f32 v93, v102, v103
	v_cvt_pk_bf16_f32 v94, v104, v105
	v_cvt_pk_bf16_f32 v95, v106, v95
	global_store_dwordx4 v[112:113], v[92:95], off offset:256
	v_add_u32_e32 v102, 0xb0, v170
	v_ashrrev_i32_e32 v103, 31, v102
	v_lshlrev_b32_e32 v94, 16, v140
	v_mul_f32_e32 v94, v96, v94
	v_lshlrev_b32_e32 v96, 16, v141
	v_and_b32_e32 v95, 0xffff0000, v140
	v_mul_f32_e32 v96, v98, v96
	v_lshlrev_b32_e32 v98, 16, v142
	v_mul_f32_e32 v95, v97, v95
	v_and_b32_e32 v97, 0xffff0000, v141
	v_mul_f32_e32 v98, v88, v98
	v_and_b32_e32 v88, 0xffff0000, v142
	v_lshlrev_b64 v[92:93], 11, v[176:177]
	v_mul_f32_e32 v97, v99, v97
	v_mul_f32_e32 v99, v89, v88
	v_lshlrev_b32_e32 v88, 16, v143
	v_lshl_add_u64 v[92:93], s[42:43], 0, v[92:93]
	v_mul_f32_e32 v100, v90, v88
	v_and_b32_e32 v88, 0xffff0000, v143
	v_lshl_add_u64 v[92:93], v[92:93], 0, v[168:169]
	v_mul_f32_e32 v91, v91, v88
	v_cvt_pk_bf16_f32 v88, v94, v95
	v_cvt_pk_bf16_f32 v89, v96, v97
	v_cvt_pk_bf16_f32 v90, v98, v99
	v_cvt_pk_bf16_f32 v91, v100, v91
	global_store_dwordx4 v[92:93], v[88:91], off
	v_add_u32_e32 v96, 0x80, v170
	v_ashrrev_i32_e32 v97, 31, v96
	v_lshlrev_b32_e32 v88, 16, v132
	v_mul_f32_e32 v84, v84, v88
	v_and_b32_e32 v88, 0xffff0000, v132
	v_mul_f32_e32 v85, v85, v88
	v_lshlrev_b32_e32 v88, 16, v133
	v_mul_f32_e32 v86, v86, v88
	v_and_b32_e32 v88, 0xffff0000, v133
	v_mul_f32_e32 v87, v87, v88
	v_lshlrev_b32_e32 v88, 16, v134
	v_mul_f32_e32 v88, v76, v88
	v_and_b32_e32 v76, 0xffff0000, v134
	v_mul_f32_e32 v89, v77, v76
	v_lshlrev_b32_e32 v76, 16, v135
	v_mul_f32_e32 v90, v78, v76
	v_and_b32_e32 v76, 0xffff0000, v135
	v_mul_f32_e32 v79, v79, v76
	v_cvt_pk_bf16_f32 v76, v84, v85
	v_cvt_pk_bf16_f32 v77, v86, v87
	v_cvt_pk_bf16_f32 v78, v88, v89
	v_cvt_pk_bf16_f32 v79, v90, v79
	global_store_dwordx4 v[92:93], v[76:79], off offset:256
	v_add_u32_e32 v98, 0x90, v170
	v_ashrrev_i32_e32 v99, 31, v98
	v_lshlrev_b32_e32 v78, 16, v136
	v_mul_f32_e32 v78, v80, v78
	v_lshlrev_b32_e32 v80, 16, v137
	v_and_b32_e32 v79, 0xffff0000, v136
	v_mul_f32_e32 v80, v82, v80
	v_lshlrev_b32_e32 v82, 16, v138
	v_mul_f32_e32 v79, v81, v79
	v_and_b32_e32 v81, 0xffff0000, v137
	v_mul_f32_e32 v82, v72, v82
	v_and_b32_e32 v72, 0xffff0000, v138
	v_lshlrev_b64 v[76:77], 11, v[174:175]
	v_mul_f32_e32 v81, v83, v81
	v_mul_f32_e32 v83, v73, v72
	v_lshlrev_b32_e32 v72, 16, v139
	v_lshl_add_u64 v[76:77], s[42:43], 0, v[76:77]
	v_mul_f32_e32 v84, v74, v72
	v_and_b32_e32 v72, 0xffff0000, v139
	v_lshl_add_u64 v[76:77], v[76:77], 0, v[168:169]
	v_mul_f32_e32 v75, v75, v72
	v_cvt_pk_bf16_f32 v72, v78, v79
	v_cvt_pk_bf16_f32 v73, v80, v81
	v_cvt_pk_bf16_f32 v74, v82, v83
	v_cvt_pk_bf16_f32 v75, v84, v75
	global_store_dwordx4 v[76:77], v[72:75], off
	v_add_u32_e32 v100, 0xa0, v170
	v_ashrrev_i32_e32 v101, 31, v100
	v_lshlrev_b32_e32 v72, 16, v128
	v_mul_f32_e32 v68, v68, v72
	v_and_b32_e32 v72, 0xffff0000, v128
	v_mul_f32_e32 v69, v69, v72
	v_lshlrev_b32_e32 v72, 16, v129
	v_mul_f32_e32 v70, v70, v72
	v_and_b32_e32 v72, 0xffff0000, v129
	v_mul_f32_e32 v71, v71, v72
	v_lshlrev_b32_e32 v72, 16, v130
	v_mul_f32_e32 v72, v64, v72
	v_and_b32_e32 v64, 0xffff0000, v130
	v_mul_f32_e32 v73, v65, v64
	v_lshlrev_b32_e32 v64, 16, v131
	v_mul_f32_e32 v74, v66, v64
	v_and_b32_e32 v64, 0xffff0000, v131
	v_mul_f32_e32 v67, v67, v64
	v_cvt_pk_bf16_f32 v64, v68, v69
	v_cvt_pk_bf16_f32 v65, v70, v71
	v_cvt_pk_bf16_f32 v66, v72, v73
	v_cvt_pk_bf16_f32 v67, v74, v67
	global_store_dwordx4 v[76:77], v[64:67], off offset:256
	v_lshlrev_b64 v[72:73], 12, v[98:99]
	v_lshl_add_u64 v[76:77], v[172:173], 0, v[72:73]
	v_lshlrev_b64 v[64:65], 12, v[96:97]
	v_lshl_add_u64 v[68:69], v[172:173], 0, v[64:65]
	s_waitcnt vmcnt(8)
	v_mov_b32_e32 v64, v196
	v_mov_b32_e32 v65, v197
	v_mov_b32_e32 v66, v198
	v_mov_b32_e32 v67, v199
	s_nop 0
	v_mov_b32_e32 v68, v204
	v_mov_b32_e32 v69, v205
	v_mov_b32_e32 v70, v206
	v_mov_b32_e32 v71, v207
	s_nop 0
	v_mov_b32_e32 v72, v208
	v_mov_b32_e32 v73, v209
	v_mov_b32_e32 v74, v210
	v_mov_b32_e32 v75, v211
	s_nop 0
	v_mov_b32_e32 v76, v212
	v_mov_b32_e32 v77, v213
	v_mov_b32_e32 v78, v214
	v_mov_b32_e32 v79, v215
	v_lshlrev_b64 v[80:81], 12, v[100:101]
	v_lshl_add_u64 v[84:85], v[172:173], 0, v[80:81]
	v_mov_b32_e32 v80, v216
	v_mov_b32_e32 v81, v217
	v_mov_b32_e32 v82, v218
	v_mov_b32_e32 v83, v219
	s_nop 0
	v_mov_b32_e32 v84, v220
	v_mov_b32_e32 v85, v221
	v_mov_b32_e32 v86, v222
	v_mov_b32_e32 v87, v223
	v_lshlrev_b64 v[88:89], 12, v[102:103]
	v_lshl_add_u64 v[92:93], v[172:173], 0, v[88:89]
	v_mov_b32_e32 v88, v224
	v_mov_b32_e32 v89, v225
	v_mov_b32_e32 v90, v226
	v_mov_b32_e32 v91, v227
	s_nop 0
	v_mov_b32_e32 v92, v228
	v_mov_b32_e32 v93, v229
	v_mov_b32_e32 v94, v230
	v_mov_b32_e32 v95, v231
	v_lshlrev_b64 v[96:97], 11, v[96:97]
	v_lshl_add_u64 v[96:97], s[42:43], 0, v[96:97]
	v_lshl_add_u64 v[96:97], v[96:97], 0, v[168:169]
	s_nop 0
	v_lshlrev_b32_e32 v104, 16, v64
	v_and_b32_e32 v64, 0xffff0000, v64
	v_mul_f32_e32 v61, v61, v64
	v_lshlrev_b32_e32 v64, 16, v65
	v_mul_f32_e32 v62, v62, v64
	v_and_b32_e32 v64, 0xffff0000, v65
	v_mul_f32_e32 v63, v63, v64
	v_lshlrev_b32_e32 v64, 16, v66
	v_mul_f32_e32 v64, v56, v64
	v_and_b32_e32 v56, 0xffff0000, v66
	v_mul_f32_e32 v65, v57, v56
	v_lshlrev_b32_e32 v56, 16, v67
	v_mul_f32_e32 v66, v58, v56
	v_and_b32_e32 v56, 0xffff0000, v67
	v_mul_f32_e32 v60, v60, v104
	v_mul_f32_e32 v59, v59, v56
	v_cvt_pk_bf16_f32 v56, v60, v61
	v_cvt_pk_bf16_f32 v57, v62, v63
	v_cvt_pk_bf16_f32 v58, v64, v65
	v_cvt_pk_bf16_f32 v59, v66, v59
	global_store_dwordx4 v[96:97], v[56:59], off
	s_nop 0
	s_nop 0
	v_lshlrev_b32_e32 v56, 16, v68
	v_mul_f32_e32 v52, v52, v56
	v_and_b32_e32 v56, 0xffff0000, v68
	v_mul_f32_e32 v53, v53, v56
	v_lshlrev_b32_e32 v56, 16, v69
	v_mul_f32_e32 v54, v54, v56
	v_and_b32_e32 v56, 0xffff0000, v69
	v_mul_f32_e32 v55, v55, v56
	v_lshlrev_b32_e32 v56, 16, v70
	v_mul_f32_e32 v56, v44, v56
	v_and_b32_e32 v44, 0xffff0000, v70
	v_mul_f32_e32 v57, v45, v44
	v_lshlrev_b32_e32 v44, 16, v71
	v_mul_f32_e32 v58, v46, v44
	v_and_b32_e32 v44, 0xffff0000, v71
	v_mul_f32_e32 v47, v47, v44
	v_cvt_pk_bf16_f32 v44, v52, v53
	v_cvt_pk_bf16_f32 v45, v54, v55
	v_cvt_pk_bf16_f32 v46, v56, v57
	v_cvt_pk_bf16_f32 v47, v58, v47
	global_store_dwordx4 v[96:97], v[44:47], off offset:256
	s_nop 0
	s_nop 0
	v_lshlrev_b32_e32 v46, 16, v72
	v_mul_f32_e32 v46, v48, v46
	v_lshlrev_b32_e32 v48, 16, v73
	v_and_b32_e32 v47, 0xffff0000, v72
	v_mul_f32_e32 v48, v50, v48
	v_lshlrev_b32_e32 v50, 16, v74
	v_mul_f32_e32 v47, v49, v47
	v_and_b32_e32 v49, 0xffff0000, v73
	v_mul_f32_e32 v50, v40, v50
	v_and_b32_e32 v40, 0xffff0000, v74
	v_lshlrev_b64 v[44:45], 11, v[98:99]
	v_mul_f32_e32 v49, v51, v49
	v_mul_f32_e32 v51, v41, v40
	v_lshlrev_b32_e32 v40, 16, v75
	v_lshl_add_u64 v[44:45], s[42:43], 0, v[44:45]
	v_mul_f32_e32 v52, v42, v40
	v_and_b32_e32 v40, 0xffff0000, v75
	v_lshl_add_u64 v[44:45], v[44:45], 0, v[168:169]
	v_mul_f32_e32 v43, v43, v40
	v_cvt_pk_bf16_f32 v40, v46, v47
	v_cvt_pk_bf16_f32 v41, v48, v49
	v_cvt_pk_bf16_f32 v42, v50, v51
	v_cvt_pk_bf16_f32 v43, v52, v43
	global_store_dwordx4 v[44:45], v[40:43], off
	s_nop 0
	s_nop 0
	v_lshlrev_b32_e32 v40, 16, v76
	v_mul_f32_e32 v36, v36, v40
	v_and_b32_e32 v40, 0xffff0000, v76
	v_mul_f32_e32 v37, v37, v40
	v_lshlrev_b32_e32 v40, 16, v77
	v_mul_f32_e32 v38, v38, v40
	v_and_b32_e32 v40, 0xffff0000, v77
	v_mul_f32_e32 v39, v39, v40
	v_lshlrev_b32_e32 v40, 16, v78
	v_mul_f32_e32 v40, v28, v40
	v_and_b32_e32 v28, 0xffff0000, v78
	v_mul_f32_e32 v41, v29, v28
	v_lshlrev_b32_e32 v28, 16, v79
	v_mul_f32_e32 v42, v30, v28
	v_and_b32_e32 v28, 0xffff0000, v79
	v_mul_f32_e32 v31, v31, v28
	v_cvt_pk_bf16_f32 v28, v36, v37
	v_cvt_pk_bf16_f32 v29, v38, v39
	v_cvt_pk_bf16_f32 v30, v40, v41
	v_cvt_pk_bf16_f32 v31, v42, v31
	global_store_dwordx4 v[44:45], v[28:31], off offset:256
	s_nop 0
	s_nop 0
	v_lshlrev_b32_e32 v30, 16, v80
	v_mul_f32_e32 v30, v32, v30
	v_lshlrev_b32_e32 v32, 16, v81
	v_and_b32_e32 v31, 0xffff0000, v80
	v_mul_f32_e32 v32, v34, v32
	v_lshlrev_b32_e32 v34, 16, v82
	v_mul_f32_e32 v31, v33, v31
	v_and_b32_e32 v33, 0xffff0000, v81
	v_mul_f32_e32 v34, v24, v34
	v_and_b32_e32 v24, 0xffff0000, v82
	v_lshlrev_b64 v[28:29], 11, v[100:101]
	v_mul_f32_e32 v33, v35, v33
	v_mul_f32_e32 v35, v25, v24
	v_lshlrev_b32_e32 v24, 16, v83
	v_lshl_add_u64 v[28:29], s[42:43], 0, v[28:29]
	v_mul_f32_e32 v36, v26, v24
	v_and_b32_e32 v24, 0xffff0000, v83
	v_lshl_add_u64 v[28:29], v[28:29], 0, v[168:169]
	v_mul_f32_e32 v27, v27, v24
	v_cvt_pk_bf16_f32 v24, v30, v31
	v_cvt_pk_bf16_f32 v25, v32, v33
	v_cvt_pk_bf16_f32 v26, v34, v35
	v_cvt_pk_bf16_f32 v27, v36, v27
	global_store_dwordx4 v[28:29], v[24:27], off
	s_nop 0
	s_nop 0
	v_lshlrev_b32_e32 v24, 16, v84
	v_mul_f32_e32 v20, v20, v24
	v_and_b32_e32 v24, 0xffff0000, v84
	v_mul_f32_e32 v21, v21, v24
	v_lshlrev_b32_e32 v24, 16, v85
	v_mul_f32_e32 v22, v22, v24
	v_and_b32_e32 v24, 0xffff0000, v85
	v_mul_f32_e32 v23, v23, v24
	v_lshlrev_b32_e32 v24, 16, v86
	v_mul_f32_e32 v24, v12, v24
	v_and_b32_e32 v12, 0xffff0000, v86
	v_mul_f32_e32 v25, v13, v12
	v_lshlrev_b32_e32 v12, 16, v87
	v_mul_f32_e32 v26, v14, v12
	v_and_b32_e32 v12, 0xffff0000, v87
	v_mul_f32_e32 v15, v15, v12
	v_cvt_pk_bf16_f32 v12, v20, v21
	v_cvt_pk_bf16_f32 v13, v22, v23
	v_cvt_pk_bf16_f32 v14, v24, v25
	v_cvt_pk_bf16_f32 v15, v26, v15
	global_store_dwordx4 v[28:29], v[12:15], off offset:256
	s_nop 0
	s_nop 0
	v_lshlrev_b32_e32 v14, 16, v88
	v_mul_f32_e32 v14, v16, v14
	v_lshlrev_b32_e32 v16, 16, v89
	v_and_b32_e32 v15, 0xffff0000, v88
	v_mul_f32_e32 v16, v18, v16
	v_lshlrev_b32_e32 v18, 16, v90
	v_mul_f32_e32 v15, v17, v15
	v_and_b32_e32 v17, 0xffff0000, v89
	v_mul_f32_e32 v18, v8, v18
	v_and_b32_e32 v8, 0xffff0000, v90
	v_lshlrev_b64 v[12:13], 11, v[102:103]
	v_mul_f32_e32 v17, v19, v17
	v_mul_f32_e32 v19, v9, v8
	v_lshlrev_b32_e32 v8, 16, v91
	v_lshl_add_u64 v[12:13], s[42:43], 0, v[12:13]
	v_mul_f32_e32 v20, v10, v8
	v_and_b32_e32 v8, 0xffff0000, v91
	v_lshl_add_u64 v[12:13], v[12:13], 0, v[168:169]
	v_mul_f32_e32 v11, v11, v8
	v_cvt_pk_bf16_f32 v8, v14, v15
	v_cvt_pk_bf16_f32 v9, v16, v17
	v_cvt_pk_bf16_f32 v10, v18, v19
	v_cvt_pk_bf16_f32 v11, v20, v11
	global_store_dwordx4 v[12:13], v[8:11], off
	s_nop 0
	s_nop 0
	v_lshlrev_b32_e32 v8, 16, v92
	v_mul_f32_e32 v4, v4, v8
	v_and_b32_e32 v8, 0xffff0000, v92
	v_mul_f32_e32 v5, v5, v8
	v_lshlrev_b32_e32 v8, 16, v93
	v_mul_f32_e32 v6, v6, v8
	v_and_b32_e32 v8, 0xffff0000, v93
	v_mul_f32_e32 v7, v7, v8
	v_lshlrev_b32_e32 v8, 16, v94
	v_mul_f32_e32 v8, v0, v8
	v_and_b32_e32 v0, 0xffff0000, v94
	v_mul_f32_e32 v9, v1, v0
	v_lshlrev_b32_e32 v0, 16, v95
	v_mul_f32_e32 v10, v2, v0
	v_and_b32_e32 v0, 0xffff0000, v95
	v_mul_f32_e32 v3, v3, v0
	v_cvt_pk_bf16_f32 v0, v4, v5
	v_cvt_pk_bf16_f32 v1, v6, v7
	v_cvt_pk_bf16_f32 v2, v8, v9
	v_cvt_pk_bf16_f32 v3, v10, v3
	global_store_dwordx4 v[12:13], v[0:3], off offset:256
	s_mov_b32 s99, 1
	s_cbranch_vccnz .LBB0_1405
	s_andn2_b64 vcc, exec, s[0:1]
	s_cbranch_vccnz .LBB0_1404
	s_barrier
	s_branch .LBB0_1404

.LBB0_2277:
	s_lshl_b32 s9, s36, 8
	v_mov_b32_e32 v128, v178
	v_mov_b32_e32 v129, v179
	s_add_i32 s9, s9, s70
	s_andn2_b64 vcc, exec, s[10:11]
	v_add_u32_e32 v170, s9, v128
	s_lshl_b32 s9, s37, 8
	s_or_b32 s9, s9, s71
	v_lshl_add_u32 v128, v129, 3, s9
	v_ashrrev_i32_e32 v129, 31, v128
	v_lshlrev_b64 v[168:169], 1, v[128:129]
	v_ashrrev_i32_e32 v171, 31, v170
	v_lshl_add_u64 v[172:173], s[56:57], 0, v[168:169]
	v_lshlrev_b64 v[128:129], 12, v[170:171]
	v_lshl_add_u64 v[128:129], v[172:173], 0, v[128:129]
	global_load_dwordx4 v[184:187], v[128:129], off
	global_load_dwordx4 v[188:191], v[128:129], off offset:256
	v_add_u32_e32 v192, 16, v170
	v_ashrrev_i32_e32 v193, 31, v192
	v_lshlrev_b64 v[128:129], 12, v[192:193]
	v_lshl_add_u64 v[128:129], v[172:173], 0, v[128:129]
	global_load_dwordx4 v[148:151], v[128:129], off
	global_load_dwordx4 v[144:147], v[128:129], off offset:256
	v_add_u32_e32 v176, 32, v170
	v_ashrrev_i32_e32 v177, 31, v176
	v_lshlrev_b64 v[128:129], 12, v[176:177]
	v_lshl_add_u64 v[128:129], v[172:173], 0, v[128:129]
	global_load_dwordx4 v[140:143], v[128:129], off
	global_load_dwordx4 v[132:135], v[128:129], off offset:256
	v_add_u32_e32 v174, 48, v170
	v_ashrrev_i32_e32 v175, 31, v174
	v_lshlrev_b64 v[128:129], 12, v[174:175]
	v_lshl_add_u64 v[128:129], v[172:173], 0, v[128:129]
	global_load_dwordx4 v[136:139], v[128:129], off
	s_nop 0
	global_load_dwordx4 v[128:131], v[128:129], off offset:256
	v_lshlrev_b64 v[194:195], 11, v[170:171]
	v_lshl_add_u64 v[194:195], s[42:43], 0, v[194:195]
	v_lshl_add_u64 v[194:195], v[194:195], 0, v[168:169]
	s_mov_b64 s[36:37], -1
	v_add_u32_e32 v200, 0x80, v170
	v_ashrrev_i32_e32 v201, 31, v200
	v_lshlrev_b64 v[252:253], 12, v[200:201]
	v_lshl_add_u64 v[200:201], v[172:173], 0, v[252:253]
	global_load_dwordx4 v[196:199], v[200:201], off
	global_load_dwordx4 v[204:207], v[200:201], off offset:256
	v_add_u32_e32 v200, 0x90, v170
	v_ashrrev_i32_e32 v201, 31, v200
	v_lshlrev_b64 v[252:253], 12, v[200:201]
	v_lshl_add_u64 v[200:201], v[172:173], 0, v[252:253]
	global_load_dwordx4 v[208:211], v[200:201], off
	global_load_dwordx4 v[212:215], v[200:201], off offset:256
	v_add_u32_e32 v200, 0xa0, v170
	v_ashrrev_i32_e32 v201, 31, v200
	v_lshlrev_b64 v[252:253], 12, v[200:201]
	v_lshl_add_u64 v[200:201], v[172:173], 0, v[252:253]
	global_load_dwordx4 v[216:219], v[200:201], off
	global_load_dwordx4 v[220:223], v[200:201], off offset:256
	v_add_u32_e32 v200, 0xb0, v170
	v_ashrrev_i32_e32 v201, 31, v200
	v_lshlrev_b64 v[252:253], 12, v[200:201]
	v_lshl_add_u64 v[200:201], v[172:173], 0, v[252:253]
	global_load_dwordx4 v[224:227], v[200:201], off
	global_load_dwordx4 v[228:231], v[200:201], off offset:256
	s_waitcnt vmcnt(8)
	v_lshlrev_b32_e32 v171, 16, v184
	v_mul_f32_e32 v124, v124, v171
	v_and_b32_e32 v171, 0xffff0000, v184
	v_mul_f32_e32 v125, v125, v171
	v_lshlrev_b32_e32 v171, 16, v185
	v_mul_f32_e32 v126, v126, v171
	v_and_b32_e32 v171, 0xffff0000, v185
	v_mul_f32_e32 v127, v127, v171
	v_lshlrev_b32_e32 v171, 16, v186
	v_mul_f32_e32 v171, v120, v171
	v_and_b32_e32 v120, 0xffff0000, v186
	v_mul_f32_e32 v184, v121, v120
	v_lshlrev_b32_e32 v120, 16, v187
	v_mul_f32_e32 v185, v122, v120
	v_and_b32_e32 v120, 0xffff0000, v187
	v_mul_f32_e32 v123, v123, v120
	v_cvt_pk_bf16_f32 v120, v124, v125
	v_cvt_pk_bf16_f32 v121, v126, v127
	v_cvt_pk_bf16_f32 v122, v171, v184
	v_cvt_pk_bf16_f32 v123, v185, v123
	global_store_dwordx4 v[194:195], v[120:123], off
	s_nop 1
	v_lshlrev_b32_e32 v120, 16, v188
	v_mul_f32_e32 v116, v116, v120
	v_and_b32_e32 v120, 0xffff0000, v188
	v_mul_f32_e32 v117, v117, v120
	v_lshlrev_b32_e32 v120, 16, v189
	v_mul_f32_e32 v118, v118, v120
	v_and_b32_e32 v120, 0xffff0000, v189
	v_mul_f32_e32 v119, v119, v120
	v_lshlrev_b32_e32 v120, 16, v190
	v_mul_f32_e32 v120, v112, v120
	v_and_b32_e32 v112, 0xffff0000, v190
	v_mul_f32_e32 v121, v113, v112
	v_lshlrev_b32_e32 v112, 16, v191
	v_mul_f32_e32 v122, v114, v112
	v_and_b32_e32 v112, 0xffff0000, v191
	v_mul_f32_e32 v115, v115, v112
	v_cvt_pk_bf16_f32 v112, v116, v117
	v_cvt_pk_bf16_f32 v113, v118, v119
	v_cvt_pk_bf16_f32 v114, v120, v121
	v_cvt_pk_bf16_f32 v115, v122, v115
	global_store_dwordx4 v[194:195], v[112:115], off offset:256
	s_nop 1
	v_lshlrev_b32_e32 v114, 16, v148
	v_mul_f32_e32 v108, v108, v114
	v_and_b32_e32 v114, 0xffff0000, v148
	v_mul_f32_e32 v109, v109, v114
	v_lshlrev_b32_e32 v114, 16, v149
	v_mul_f32_e32 v110, v110, v114
	v_and_b32_e32 v114, 0xffff0000, v149
	v_mul_f32_e32 v111, v111, v114
	v_lshlrev_b32_e32 v114, 16, v150
	v_mul_f32_e32 v114, v104, v114
	v_and_b32_e32 v104, 0xffff0000, v150
	v_lshlrev_b64 v[112:113], 11, v[192:193]
	v_mul_f32_e32 v115, v105, v104
	v_lshlrev_b32_e32 v104, 16, v151
	v_lshl_add_u64 v[112:113], s[42:43], 0, v[112:113]
	v_mul_f32_e32 v116, v106, v104
	v_and_b32_e32 v104, 0xffff0000, v151
	v_lshl_add_u64 v[112:113], v[112:113], 0, v[168:169]
	v_mul_f32_e32 v107, v107, v104
	v_cvt_pk_bf16_f32 v104, v108, v109
	v_cvt_pk_bf16_f32 v105, v110, v111
	v_cvt_pk_bf16_f32 v106, v114, v115
	v_cvt_pk_bf16_f32 v107, v116, v107
	global_store_dwordx4 v[112:113], v[104:107], off
	s_nop 1
	v_lshlrev_b32_e32 v104, 16, v144
	v_mul_f32_e32 v100, v100, v104
	v_and_b32_e32 v104, 0xffff0000, v144
	v_mul_f32_e32 v101, v101, v104
	v_lshlrev_b32_e32 v104, 16, v145
	v_mul_f32_e32 v102, v102, v104
	v_and_b32_e32 v104, 0xffff0000, v145
	v_mul_f32_e32 v103, v103, v104
	v_lshlrev_b32_e32 v104, 16, v146
	v_mul_f32_e32 v104, v92, v104
	v_and_b32_e32 v92, 0xffff0000, v146
	v_mul_f32_e32 v105, v93, v92
	v_lshlrev_b32_e32 v92, 16, v147
	v_mul_f32_e32 v106, v94, v92
	v_and_b32_e32 v92, 0xffff0000, v147
	v_mul_f32_e32 v95, v95, v92
	v_cvt_pk_bf16_f32 v92, v100, v101
	v_cvt_pk_bf16_f32 v93, v102, v103
	v_cvt_pk_bf16_f32 v94, v104, v105
	v_cvt_pk_bf16_f32 v95, v106, v95
	global_store_dwordx4 v[112:113], v[92:95], off offset:256
	v_add_u32_e32 v102, 0xb0, v170
	v_ashrrev_i32_e32 v103, 31, v102
	v_lshlrev_b32_e32 v94, 16, v140
	v_mul_f32_e32 v94, v96, v94
	v_lshlrev_b32_e32 v96, 16, v141
	v_and_b32_e32 v95, 0xffff0000, v140
	v_mul_f32_e32 v96, v98, v96
	v_lshlrev_b32_e32 v98, 16, v142
	v_mul_f32_e32 v95, v97, v95
	v_and_b32_e32 v97, 0xffff0000, v141
	v_mul_f32_e32 v98, v88, v98
	v_and_b32_e32 v88, 0xffff0000, v142
	v_lshlrev_b64 v[92:93], 11, v[176:177]
	v_mul_f32_e32 v97, v99, v97
	v_mul_f32_e32 v99, v89, v88
	v_lshlrev_b32_e32 v88, 16, v143
	v_lshl_add_u64 v[92:93], s[42:43], 0, v[92:93]
	v_mul_f32_e32 v100, v90, v88
	v_and_b32_e32 v88, 0xffff0000, v143
	v_lshl_add_u64 v[92:93], v[92:93], 0, v[168:169]
	v_mul_f32_e32 v91, v91, v88
	v_cvt_pk_bf16_f32 v88, v94, v95
	v_cvt_pk_bf16_f32 v89, v96, v97
	v_cvt_pk_bf16_f32 v90, v98, v99
	v_cvt_pk_bf16_f32 v91, v100, v91
	global_store_dwordx4 v[92:93], v[88:91], off
	v_add_u32_e32 v96, 0x80, v170
	v_ashrrev_i32_e32 v97, 31, v96
	v_lshlrev_b32_e32 v88, 16, v132
	v_mul_f32_e32 v84, v84, v88
	v_and_b32_e32 v88, 0xffff0000, v132
	v_mul_f32_e32 v85, v85, v88
	v_lshlrev_b32_e32 v88, 16, v133
	v_mul_f32_e32 v86, v86, v88
	v_and_b32_e32 v88, 0xffff0000, v133
	v_mul_f32_e32 v87, v87, v88
	v_lshlrev_b32_e32 v88, 16, v134
	v_mul_f32_e32 v88, v76, v88
	v_and_b32_e32 v76, 0xffff0000, v134
	v_mul_f32_e32 v89, v77, v76
	v_lshlrev_b32_e32 v76, 16, v135
	v_mul_f32_e32 v90, v78, v76
	v_and_b32_e32 v76, 0xffff0000, v135
	v_mul_f32_e32 v79, v79, v76
	v_cvt_pk_bf16_f32 v76, v84, v85
	v_cvt_pk_bf16_f32 v77, v86, v87
	v_cvt_pk_bf16_f32 v78, v88, v89
	v_cvt_pk_bf16_f32 v79, v90, v79
	global_store_dwordx4 v[92:93], v[76:79], off offset:256
	v_add_u32_e32 v98, 0x90, v170
	v_ashrrev_i32_e32 v99, 31, v98
	v_lshlrev_b32_e32 v78, 16, v136
	v_mul_f32_e32 v78, v80, v78
	v_lshlrev_b32_e32 v80, 16, v137
	v_and_b32_e32 v79, 0xffff0000, v136
	v_mul_f32_e32 v80, v82, v80
	v_lshlrev_b32_e32 v82, 16, v138
	v_mul_f32_e32 v79, v81, v79
	v_and_b32_e32 v81, 0xffff0000, v137
	v_mul_f32_e32 v82, v72, v82
	v_and_b32_e32 v72, 0xffff0000, v138
	v_lshlrev_b64 v[76:77], 11, v[174:175]
	v_mul_f32_e32 v81, v83, v81
	v_mul_f32_e32 v83, v73, v72
	v_lshlrev_b32_e32 v72, 16, v139
	v_lshl_add_u64 v[76:77], s[42:43], 0, v[76:77]
	v_mul_f32_e32 v84, v74, v72
	v_and_b32_e32 v72, 0xffff0000, v139
	v_lshl_add_u64 v[76:77], v[76:77], 0, v[168:169]
	v_mul_f32_e32 v75, v75, v72
	v_cvt_pk_bf16_f32 v72, v78, v79
	v_cvt_pk_bf16_f32 v73, v80, v81
	v_cvt_pk_bf16_f32 v74, v82, v83
	v_cvt_pk_bf16_f32 v75, v84, v75
	global_store_dwordx4 v[76:77], v[72:75], off
	v_add_u32_e32 v100, 0xa0, v170
	v_ashrrev_i32_e32 v101, 31, v100
	v_lshlrev_b32_e32 v72, 16, v128
	v_mul_f32_e32 v68, v68, v72
	v_and_b32_e32 v72, 0xffff0000, v128
	v_mul_f32_e32 v69, v69, v72
	v_lshlrev_b32_e32 v72, 16, v129
	v_mul_f32_e32 v70, v70, v72
	v_and_b32_e32 v72, 0xffff0000, v129
	v_mul_f32_e32 v71, v71, v72
	v_lshlrev_b32_e32 v72, 16, v130
	v_mul_f32_e32 v72, v64, v72
	v_and_b32_e32 v64, 0xffff0000, v130
	v_mul_f32_e32 v73, v65, v64
	v_lshlrev_b32_e32 v64, 16, v131
	v_mul_f32_e32 v74, v66, v64
	v_and_b32_e32 v64, 0xffff0000, v131
	v_mul_f32_e32 v67, v67, v64
	v_cvt_pk_bf16_f32 v64, v68, v69
	v_cvt_pk_bf16_f32 v65, v70, v71
	v_cvt_pk_bf16_f32 v66, v72, v73
	v_cvt_pk_bf16_f32 v67, v74, v67
	global_store_dwordx4 v[76:77], v[64:67], off offset:256
	v_lshlrev_b64 v[72:73], 12, v[98:99]
	v_lshl_add_u64 v[76:77], v[172:173], 0, v[72:73]
	v_lshlrev_b64 v[64:65], 12, v[96:97]
	v_lshl_add_u64 v[68:69], v[172:173], 0, v[64:65]
	s_waitcnt vmcnt(8)
	v_mov_b32_e32 v64, v196
	v_mov_b32_e32 v65, v197
	v_mov_b32_e32 v66, v198
	v_mov_b32_e32 v67, v199
	s_nop 0
	v_mov_b32_e32 v68, v204
	v_mov_b32_e32 v69, v205
	v_mov_b32_e32 v70, v206
	v_mov_b32_e32 v71, v207
	s_nop 0
	v_mov_b32_e32 v72, v208
	v_mov_b32_e32 v73, v209
	v_mov_b32_e32 v74, v210
	v_mov_b32_e32 v75, v211
	s_nop 0
	v_mov_b32_e32 v76, v212
	v_mov_b32_e32 v77, v213
	v_mov_b32_e32 v78, v214
	v_mov_b32_e32 v79, v215
	v_lshlrev_b64 v[80:81], 12, v[100:101]
	v_lshl_add_u64 v[84:85], v[172:173], 0, v[80:81]
	v_mov_b32_e32 v80, v216
	v_mov_b32_e32 v81, v217
	v_mov_b32_e32 v82, v218
	v_mov_b32_e32 v83, v219
	s_nop 0
	v_mov_b32_e32 v84, v220
	v_mov_b32_e32 v85, v221
	v_mov_b32_e32 v86, v222
	v_mov_b32_e32 v87, v223
	v_lshlrev_b64 v[88:89], 12, v[102:103]
	v_lshl_add_u64 v[92:93], v[172:173], 0, v[88:89]
	v_mov_b32_e32 v88, v224
	v_mov_b32_e32 v89, v225
	v_mov_b32_e32 v90, v226
	v_mov_b32_e32 v91, v227
	s_nop 0
	v_mov_b32_e32 v92, v228
	v_mov_b32_e32 v93, v229
	v_mov_b32_e32 v94, v230
	v_mov_b32_e32 v95, v231
	v_lshlrev_b64 v[96:97], 11, v[96:97]
	v_lshl_add_u64 v[96:97], s[42:43], 0, v[96:97]
	v_lshl_add_u64 v[96:97], v[96:97], 0, v[168:169]
	s_nop 0
	v_lshlrev_b32_e32 v104, 16, v64
	v_and_b32_e32 v64, 0xffff0000, v64
	v_mul_f32_e32 v61, v61, v64
	v_lshlrev_b32_e32 v64, 16, v65
	v_mul_f32_e32 v62, v62, v64
	v_and_b32_e32 v64, 0xffff0000, v65
	v_mul_f32_e32 v63, v63, v64
	v_lshlrev_b32_e32 v64, 16, v66
	v_mul_f32_e32 v64, v56, v64
	v_and_b32_e32 v56, 0xffff0000, v66
	v_mul_f32_e32 v65, v57, v56
	v_lshlrev_b32_e32 v56, 16, v67
	v_mul_f32_e32 v66, v58, v56
	v_and_b32_e32 v56, 0xffff0000, v67
	v_mul_f32_e32 v60, v60, v104
	v_mul_f32_e32 v59, v59, v56
	v_cvt_pk_bf16_f32 v56, v60, v61
	v_cvt_pk_bf16_f32 v57, v62, v63
	v_cvt_pk_bf16_f32 v58, v64, v65
	v_cvt_pk_bf16_f32 v59, v66, v59
	global_store_dwordx4 v[96:97], v[56:59], off
	s_nop 0
	s_nop 0
	v_lshlrev_b32_e32 v56, 16, v68
	v_mul_f32_e32 v52, v52, v56
	v_and_b32_e32 v56, 0xffff0000, v68
	v_mul_f32_e32 v53, v53, v56
	v_lshlrev_b32_e32 v56, 16, v69
	v_mul_f32_e32 v54, v54, v56
	v_and_b32_e32 v56, 0xffff0000, v69
	v_mul_f32_e32 v55, v55, v56
	v_lshlrev_b32_e32 v56, 16, v70
	v_mul_f32_e32 v56, v44, v56
	v_and_b32_e32 v44, 0xffff0000, v70
	v_mul_f32_e32 v57, v45, v44
	v_lshlrev_b32_e32 v44, 16, v71
	v_mul_f32_e32 v58, v46, v44
	v_and_b32_e32 v44, 0xffff0000, v71
	v_mul_f32_e32 v47, v47, v44
	v_cvt_pk_bf16_f32 v44, v52, v53
	v_cvt_pk_bf16_f32 v45, v54, v55
	v_cvt_pk_bf16_f32 v46, v56, v57
	v_cvt_pk_bf16_f32 v47, v58, v47
	global_store_dwordx4 v[96:97], v[44:47], off offset:256
	s_nop 0
	s_nop 0
	v_lshlrev_b32_e32 v46, 16, v72
	v_mul_f32_e32 v46, v48, v46
	v_lshlrev_b32_e32 v48, 16, v73
	v_and_b32_e32 v47, 0xffff0000, v72
	v_mul_f32_e32 v48, v50, v48
	v_lshlrev_b32_e32 v50, 16, v74
	v_mul_f32_e32 v47, v49, v47
	v_and_b32_e32 v49, 0xffff0000, v73
	v_mul_f32_e32 v50, v40, v50
	v_and_b32_e32 v40, 0xffff0000, v74
	v_lshlrev_b64 v[44:45], 11, v[98:99]
	v_mul_f32_e32 v49, v51, v49
	v_mul_f32_e32 v51, v41, v40
	v_lshlrev_b32_e32 v40, 16, v75
	v_lshl_add_u64 v[44:45], s[42:43], 0, v[44:45]
	v_mul_f32_e32 v52, v42, v40
	v_and_b32_e32 v40, 0xffff0000, v75
	v_lshl_add_u64 v[44:45], v[44:45], 0, v[168:169]
	v_mul_f32_e32 v43, v43, v40
	v_cvt_pk_bf16_f32 v40, v46, v47
	v_cvt_pk_bf16_f32 v41, v48, v49
	v_cvt_pk_bf16_f32 v42, v50, v51
	v_cvt_pk_bf16_f32 v43, v52, v43
	global_store_dwordx4 v[44:45], v[40:43], off
	s_nop 0
	s_nop 0
	v_lshlrev_b32_e32 v40, 16, v76
	v_mul_f32_e32 v36, v36, v40
	v_and_b32_e32 v40, 0xffff0000, v76
	v_mul_f32_e32 v37, v37, v40
	v_lshlrev_b32_e32 v40, 16, v77
	v_mul_f32_e32 v38, v38, v40
	v_and_b32_e32 v40, 0xffff0000, v77
	v_mul_f32_e32 v39, v39, v40
	v_lshlrev_b32_e32 v40, 16, v78
	v_mul_f32_e32 v40, v28, v40
	v_and_b32_e32 v28, 0xffff0000, v78
	v_mul_f32_e32 v41, v29, v28
	v_lshlrev_b32_e32 v28, 16, v79
	v_mul_f32_e32 v42, v30, v28
	v_and_b32_e32 v28, 0xffff0000, v79
	v_mul_f32_e32 v31, v31, v28
	v_cvt_pk_bf16_f32 v28, v36, v37
	v_cvt_pk_bf16_f32 v29, v38, v39
	v_cvt_pk_bf16_f32 v30, v40, v41
	v_cvt_pk_bf16_f32 v31, v42, v31
	global_store_dwordx4 v[44:45], v[28:31], off offset:256
	s_nop 0
	s_nop 0
	v_lshlrev_b32_e32 v30, 16, v80
	v_mul_f32_e32 v30, v32, v30
	v_lshlrev_b32_e32 v32, 16, v81
	v_and_b32_e32 v31, 0xffff0000, v80
	v_mul_f32_e32 v32, v34, v32
	v_lshlrev_b32_e32 v34, 16, v82
	v_mul_f32_e32 v31, v33, v31
	v_and_b32_e32 v33, 0xffff0000, v81
	v_mul_f32_e32 v34, v24, v34
	v_and_b32_e32 v24, 0xffff0000, v82
	v_lshlrev_b64 v[28:29], 11, v[100:101]
	v_mul_f32_e32 v33, v35, v33
	v_mul_f32_e32 v35, v25, v24
	v_lshlrev_b32_e32 v24, 16, v83
	v_lshl_add_u64 v[28:29], s[42:43], 0, v[28:29]
	v_mul_f32_e32 v36, v26, v24
	v_and_b32_e32 v24, 0xffff0000, v83
	v_lshl_add_u64 v[28:29], v[28:29], 0, v[168:169]
	v_mul_f32_e32 v27, v27, v24
	v_cvt_pk_bf16_f32 v24, v30, v31
	v_cvt_pk_bf16_f32 v25, v32, v33
	v_cvt_pk_bf16_f32 v26, v34, v35
	v_cvt_pk_bf16_f32 v27, v36, v27
	global_store_dwordx4 v[28:29], v[24:27], off
	s_nop 0
	s_nop 0
	v_lshlrev_b32_e32 v24, 16, v84
	v_mul_f32_e32 v20, v20, v24
	v_and_b32_e32 v24, 0xffff0000, v84
	v_mul_f32_e32 v21, v21, v24
	v_lshlrev_b32_e32 v24, 16, v85
	v_mul_f32_e32 v22, v22, v24
	v_and_b32_e32 v24, 0xffff0000, v85
	v_mul_f32_e32 v23, v23, v24
	v_lshlrev_b32_e32 v24, 16, v86
	v_mul_f32_e32 v24, v12, v24
	v_and_b32_e32 v12, 0xffff0000, v86
	v_mul_f32_e32 v25, v13, v12
	v_lshlrev_b32_e32 v12, 16, v87
	v_mul_f32_e32 v26, v14, v12
	v_and_b32_e32 v12, 0xffff0000, v87
	v_mul_f32_e32 v15, v15, v12
	v_cvt_pk_bf16_f32 v12, v20, v21
	v_cvt_pk_bf16_f32 v13, v22, v23
	v_cvt_pk_bf16_f32 v14, v24, v25
	v_cvt_pk_bf16_f32 v15, v26, v15
	global_store_dwordx4 v[28:29], v[12:15], off offset:256
	s_nop 0
	s_nop 0
	v_lshlrev_b32_e32 v14, 16, v88
	v_mul_f32_e32 v14, v16, v14
	v_lshlrev_b32_e32 v16, 16, v89
	v_and_b32_e32 v15, 0xffff0000, v88
	v_mul_f32_e32 v16, v18, v16
	v_lshlrev_b32_e32 v18, 16, v90
	v_mul_f32_e32 v15, v17, v15
	v_and_b32_e32 v17, 0xffff0000, v89
	v_mul_f32_e32 v18, v8, v18
	v_and_b32_e32 v8, 0xffff0000, v90
	v_lshlrev_b64 v[12:13], 11, v[102:103]
	v_mul_f32_e32 v17, v19, v17
	v_mul_f32_e32 v19, v9, v8
	v_lshlrev_b32_e32 v8, 16, v91
	v_lshl_add_u64 v[12:13], s[42:43], 0, v[12:13]
	v_mul_f32_e32 v20, v10, v8
	v_and_b32_e32 v8, 0xffff0000, v91
	v_lshl_add_u64 v[12:13], v[12:13], 0, v[168:169]
	v_mul_f32_e32 v11, v11, v8
	v_cvt_pk_bf16_f32 v8, v14, v15
	v_cvt_pk_bf16_f32 v9, v16, v17
	v_cvt_pk_bf16_f32 v10, v18, v19
	v_cvt_pk_bf16_f32 v11, v20, v11
	global_store_dwordx4 v[12:13], v[8:11], off
	s_nop 0
	s_nop 0
	v_lshlrev_b32_e32 v8, 16, v92
	v_mul_f32_e32 v4, v4, v8
	v_and_b32_e32 v8, 0xffff0000, v92
	v_mul_f32_e32 v5, v5, v8
	v_lshlrev_b32_e32 v8, 16, v93
	v_mul_f32_e32 v6, v6, v8
	v_and_b32_e32 v8, 0xffff0000, v93
	v_mul_f32_e32 v7, v7, v8
	v_lshlrev_b32_e32 v8, 16, v94
	v_mul_f32_e32 v8, v0, v8
	v_and_b32_e32 v0, 0xffff0000, v94
	v_mul_f32_e32 v9, v1, v0
	v_lshlrev_b32_e32 v0, 16, v95
	v_mul_f32_e32 v10, v2, v0
	v_and_b32_e32 v0, 0xffff0000, v95
	v_mul_f32_e32 v3, v3, v0
	v_cvt_pk_bf16_f32 v0, v4, v5
	v_cvt_pk_bf16_f32 v1, v6, v7
	v_cvt_pk_bf16_f32 v2, v8, v9
	v_cvt_pk_bf16_f32 v3, v10, v3
	global_store_dwordx4 v[12:13], v[0:3], off offset:256
	s_mov_b32 s99, 1
	s_cbranch_vccnz .LBB0_2266
	s_andn2_b64 vcc, exec, s[0:1]
	s_cbranch_vccnz .LBB0_2265
	s_barrier
	s_branch .LBB0_2265

.LBB0_3141:
	s_lshl_b32 s11, s22, 8
	v_mov_b32_e32 v144, v150
	v_mov_b32_e32 v145, v151
	s_add_i32 s11, s11, s47
	s_andn2_b64 vcc, exec, s[6:7]
	v_add_u32_e32 v146, s11, v144
	s_lshl_b32 s11, s53, 8
	s_or_b32 s11, s11, s48
	v_lshl_add_u32 v144, v145, 3, s11
	v_ashrrev_i32_e32 v145, 31, v144
	v_lshlrev_b64 v[144:145], 1, v[144:145]
	v_ashrrev_i32_e32 v147, 31, v146
	v_lshl_add_u64 v[148:149], s[56:57], 0, v[144:145]
	v_lshlrev_b64 v[156:157], 12, v[146:147]
	v_lshl_add_u64 v[160:161], v[148:149], 0, v[156:157]
	v_add_u32_e32 v172, 16, v146
	global_load_dwordx4 v[156:159], v[160:161], off
	s_nop 0
	global_load_dwordx4 v[160:163], v[160:161], off offset:256
	v_ashrrev_i32_e32 v173, 31, v172
	v_lshlrev_b64 v[164:165], 12, v[172:173]
	v_lshl_add_u64 v[168:169], v[148:149], 0, v[164:165]
	global_load_dwordx4 v[164:167], v[168:169], off
	v_add_u32_e32 v188, 32, v146
	global_load_dwordx4 v[168:171], v[168:169], off offset:256
	v_add_u32_e32 v190, 48, v146
	v_ashrrev_i32_e32 v189, 31, v188
	v_ashrrev_i32_e32 v191, 31, v190
	v_lshlrev_b64 v[174:175], 11, v[146:147]
	v_lshlrev_b64 v[176:177], 12, v[188:189]
	v_lshlrev_b64 v[178:179], 12, v[190:191]
	v_lshl_add_u64 v[174:175], s[42:43], 0, v[174:175]
	v_lshlrev_b64 v[172:173], 11, v[172:173]
	v_lshl_add_u64 v[176:177], v[148:149], 0, v[176:177]
	v_lshl_add_u64 v[184:185], v[148:149], 0, v[178:179]
	v_lshl_add_u64 v[192:193], v[174:175], 0, v[144:145]
	v_lshl_add_u64 v[194:195], s[42:43], 0, v[172:173]
	global_load_dwordx4 v[172:175], v[176:177], off
	s_nop 0
	global_load_dwordx4 v[176:179], v[176:177], off offset:256
	s_nop 0
	global_load_dwordx4 v[180:183], v[184:185], off
	s_nop 0
	global_load_dwordx4 v[184:187], v[184:185], off offset:256
	v_lshl_add_u64 v[194:195], v[194:195], 0, v[144:145]
	s_mov_b64 s[6:7], -1
	v_add_u32_e32 v250, 0x80, v146
	v_ashrrev_i32_e32 v251, 31, v250
	v_lshlrev_b64 v[252:253], 12, v[250:251]
	v_lshl_add_u64 v[250:251], v[148:149], 0, v[252:253]
	global_load_dwordx4 v[206:209], v[250:251], off
	global_load_dwordx4 v[210:213], v[250:251], off offset:256
	v_add_u32_e32 v250, 0x90, v146
	v_ashrrev_i32_e32 v251, 31, v250
	v_lshlrev_b64 v[252:253], 12, v[250:251]
	v_lshl_add_u64 v[250:251], v[148:149], 0, v[252:253]
	global_load_dwordx4 v[214:217], v[250:251], off
	global_load_dwordx4 v[218:221], v[250:251], off offset:256
	v_add_u32_e32 v250, 0xa0, v146
	v_ashrrev_i32_e32 v251, 31, v250
	v_lshlrev_b64 v[252:253], 12, v[250:251]
	v_lshl_add_u64 v[250:251], v[148:149], 0, v[252:253]
	global_load_dwordx4 v[222:225], v[250:251], off
	global_load_dwordx4 v[226:229], v[250:251], off offset:256
	v_add_u32_e32 v250, 0xb0, v146
	v_ashrrev_i32_e32 v251, 31, v250
	v_lshlrev_b64 v[252:253], 12, v[250:251]
	v_lshl_add_u64 v[250:251], v[148:149], 0, v[252:253]
	global_load_dwordx4 v[230:233], v[250:251], off
	global_load_dwordx4 v[234:237], v[250:251], off offset:256
	s_waitcnt vmcnt(8)
	v_lshlrev_b32_e32 v147, 16, v156
	v_and_b32_e32 v156, 0xffff0000, v156
	v_lshlrev_b32_e32 v201, 16, v162
	v_lshlrev_b32_e32 v196, 16, v157
	v_and_b32_e32 v157, 0xffff0000, v157
	v_lshlrev_b32_e32 v197, 16, v158
	v_and_b32_e32 v158, 0xffff0000, v158
	v_lshlrev_b32_e32 v198, 16, v159
	v_and_b32_e32 v159, 0xffff0000, v159
	v_lshlrev_b32_e32 v199, 16, v160
	v_and_b32_e32 v160, 0xffff0000, v160
	v_and_b32_e32 v162, 0xffff0000, v162
	v_lshlrev_b32_e32 v202, 16, v163
	v_and_b32_e32 v163, 0xffff0000, v163
	v_mul_f32_e32 v124, v124, v147
	v_mul_f32_e32 v125, v125, v156
	v_mul_f32_e32 v147, v104, v201
	v_cvt_pk_bf16_f32 v104, v124, v125
	v_lshlrev_b32_e32 v200, 16, v161
	v_and_b32_e32 v161, 0xffff0000, v161
	v_mul_f32_e32 v126, v126, v196
	v_mul_f32_e32 v127, v127, v157
	v_mul_f32_e32 v120, v120, v197
	v_mul_f32_e32 v121, v121, v158
	v_mul_f32_e32 v122, v122, v198
	v_mul_f32_e32 v123, v123, v159
	v_mul_f32_e32 v112, v112, v199
	v_mul_f32_e32 v113, v113, v160
	v_mul_f32_e32 v156, v105, v162
	v_mul_f32_e32 v157, v106, v202
	v_mul_f32_e32 v158, v107, v163
	v_cvt_pk_bf16_f32 v105, v126, v127
	v_cvt_pk_bf16_f32 v106, v120, v121
	v_cvt_pk_bf16_f32 v107, v122, v123
	global_store_dwordx4 v[192:193], v[104:107], off
	v_mul_f32_e32 v114, v114, v200
	v_mul_f32_e32 v115, v115, v161
	v_cvt_pk_bf16_f32 v104, v112, v113
	v_cvt_pk_bf16_f32 v105, v114, v115
	v_cvt_pk_bf16_f32 v106, v147, v156
	v_cvt_pk_bf16_f32 v107, v157, v158
	global_store_dwordx4 v[192:193], v[104:107], off offset:256
	v_lshlrev_b32_e32 v205, 16, v166
	v_lshlrev_b32_e32 v203, 16, v164
	v_and_b32_e32 v104, 0xffff0000, v166
	v_mul_f32_e32 v107, v109, v104
	v_lshlrev_b32_e32 v104, 16, v167
	v_and_b32_e32 v164, 0xffff0000, v164
	v_mul_f32_e32 v106, v108, v205
	v_mul_f32_e32 v108, v110, v104
	v_and_b32_e32 v104, 0xffff0000, v167
	v_lshlrev_b32_e32 v204, 16, v165
	v_and_b32_e32 v165, 0xffff0000, v165
	v_mul_f32_e32 v116, v116, v203
	v_mul_f32_e32 v117, v117, v164
	v_mul_f32_e32 v109, v111, v104
	v_cvt_pk_bf16_f32 v104, v116, v117
	v_mul_f32_e32 v118, v118, v204
	v_mul_f32_e32 v119, v119, v165
	v_cvt_pk_bf16_f32 v105, v118, v119
	v_cvt_pk_bf16_f32 v106, v106, v107
	v_cvt_pk_bf16_f32 v107, v108, v109
	global_store_dwordx4 v[194:195], v[104:107], off
	s_nop 1
	v_lshlrev_b32_e32 v104, 16, v168
	v_mul_f32_e32 v100, v100, v104
	v_and_b32_e32 v104, 0xffff0000, v168
	v_mul_f32_e32 v101, v101, v104
	v_lshlrev_b32_e32 v104, 16, v169
	v_mul_f32_e32 v102, v102, v104
	v_and_b32_e32 v104, 0xffff0000, v169
	v_mul_f32_e32 v103, v103, v104
	v_lshlrev_b32_e32 v104, 16, v170
	v_mul_f32_e32 v104, v92, v104
	v_and_b32_e32 v92, 0xffff0000, v170
	v_mul_f32_e32 v105, v93, v92
	v_lshlrev_b32_e32 v92, 16, v171
	v_mul_f32_e32 v106, v94, v92
	v_and_b32_e32 v92, 0xffff0000, v171
	v_mul_f32_e32 v95, v95, v92
	v_cvt_pk_bf16_f32 v92, v100, v101
	v_cvt_pk_bf16_f32 v93, v102, v103
	v_cvt_pk_bf16_f32 v94, v104, v105
	v_cvt_pk_bf16_f32 v95, v106, v95
	global_store_dwordx4 v[194:195], v[92:95], off offset:256
	v_add_u32_e32 v102, 0xb0, v146
	v_ashrrev_i32_e32 v103, 31, v102
	v_lshlrev_b32_e32 v94, 16, v172
	v_mul_f32_e32 v94, v96, v94
	v_lshlrev_b32_e32 v96, 16, v173
	v_and_b32_e32 v95, 0xffff0000, v172
	v_mul_f32_e32 v96, v98, v96
	v_lshlrev_b32_e32 v98, 16, v174
	v_mul_f32_e32 v95, v97, v95
	v_and_b32_e32 v97, 0xffff0000, v173
	v_mul_f32_e32 v98, v88, v98
	v_and_b32_e32 v88, 0xffff0000, v174
	v_lshlrev_b64 v[92:93], 11, v[188:189]
	v_mul_f32_e32 v97, v99, v97
	v_mul_f32_e32 v99, v89, v88
	v_lshlrev_b32_e32 v88, 16, v175
	v_lshl_add_u64 v[92:93], s[42:43], 0, v[92:93]
	v_mul_f32_e32 v100, v90, v88
	v_and_b32_e32 v88, 0xffff0000, v175
	v_lshl_add_u64 v[92:93], v[92:93], 0, v[144:145]
	v_mul_f32_e32 v91, v91, v88
	v_cvt_pk_bf16_f32 v88, v94, v95
	v_cvt_pk_bf16_f32 v89, v96, v97
	v_cvt_pk_bf16_f32 v90, v98, v99
	v_cvt_pk_bf16_f32 v91, v100, v91
	global_store_dwordx4 v[92:93], v[88:91], off
	v_add_u32_e32 v96, 0x80, v146
	v_ashrrev_i32_e32 v97, 31, v96
	v_lshlrev_b32_e32 v88, 16, v176
	v_mul_f32_e32 v84, v84, v88
	v_and_b32_e32 v88, 0xffff0000, v176
	v_mul_f32_e32 v85, v85, v88
	v_lshlrev_b32_e32 v88, 16, v177
	v_mul_f32_e32 v86, v86, v88
	v_and_b32_e32 v88, 0xffff0000, v177
	v_mul_f32_e32 v87, v87, v88
	v_lshlrev_b32_e32 v88, 16, v178
	v_mul_f32_e32 v88, v76, v88
	v_and_b32_e32 v76, 0xffff0000, v178
	v_mul_f32_e32 v89, v77, v76
	v_lshlrev_b32_e32 v76, 16, v179
	v_mul_f32_e32 v90, v78, v76
	v_and_b32_e32 v76, 0xffff0000, v179
	v_mul_f32_e32 v79, v79, v76
	v_cvt_pk_bf16_f32 v76, v84, v85
	v_cvt_pk_bf16_f32 v77, v86, v87
	v_cvt_pk_bf16_f32 v78, v88, v89
	v_cvt_pk_bf16_f32 v79, v90, v79
	global_store_dwordx4 v[92:93], v[76:79], off offset:256
	v_add_u32_e32 v98, 0x90, v146
	v_ashrrev_i32_e32 v99, 31, v98
	v_lshlrev_b32_e32 v78, 16, v180
	v_mul_f32_e32 v78, v80, v78
	v_lshlrev_b32_e32 v80, 16, v181
	v_and_b32_e32 v79, 0xffff0000, v180
	v_mul_f32_e32 v80, v82, v80
	v_lshlrev_b32_e32 v82, 16, v182
	v_mul_f32_e32 v79, v81, v79
	v_and_b32_e32 v81, 0xffff0000, v181
	v_mul_f32_e32 v82, v72, v82
	v_and_b32_e32 v72, 0xffff0000, v182
	v_lshlrev_b64 v[76:77], 11, v[190:191]
	v_mul_f32_e32 v81, v83, v81
	v_mul_f32_e32 v83, v73, v72
	v_lshlrev_b32_e32 v72, 16, v183
	v_lshl_add_u64 v[76:77], s[42:43], 0, v[76:77]
	v_mul_f32_e32 v84, v74, v72
	v_and_b32_e32 v72, 0xffff0000, v183
	v_lshl_add_u64 v[76:77], v[76:77], 0, v[144:145]
	v_mul_f32_e32 v75, v75, v72
	v_cvt_pk_bf16_f32 v72, v78, v79
	v_cvt_pk_bf16_f32 v73, v80, v81
	v_cvt_pk_bf16_f32 v74, v82, v83
	v_cvt_pk_bf16_f32 v75, v84, v75
	global_store_dwordx4 v[76:77], v[72:75], off
	v_add_u32_e32 v100, 0xa0, v146
	v_ashrrev_i32_e32 v101, 31, v100
	v_lshlrev_b32_e32 v72, 16, v184
	v_mul_f32_e32 v68, v68, v72
	v_and_b32_e32 v72, 0xffff0000, v184
	v_mul_f32_e32 v69, v69, v72
	v_lshlrev_b32_e32 v72, 16, v185
	v_mul_f32_e32 v70, v70, v72
	v_and_b32_e32 v72, 0xffff0000, v185
	v_mul_f32_e32 v71, v71, v72
	v_lshlrev_b32_e32 v72, 16, v186
	v_mul_f32_e32 v72, v64, v72
	v_and_b32_e32 v64, 0xffff0000, v186
	v_mul_f32_e32 v73, v65, v64
	v_lshlrev_b32_e32 v64, 16, v187
	v_mul_f32_e32 v74, v66, v64
	v_and_b32_e32 v64, 0xffff0000, v187
	v_mul_f32_e32 v67, v67, v64
	v_cvt_pk_bf16_f32 v64, v68, v69
	v_cvt_pk_bf16_f32 v65, v70, v71
	v_cvt_pk_bf16_f32 v66, v72, v73
	v_cvt_pk_bf16_f32 v67, v74, v67
	global_store_dwordx4 v[76:77], v[64:67], off offset:256
	v_lshlrev_b64 v[72:73], 12, v[98:99]
	v_lshl_add_u64 v[76:77], v[148:149], 0, v[72:73]
	v_lshlrev_b64 v[64:65], 12, v[96:97]
	v_lshl_add_u64 v[68:69], v[148:149], 0, v[64:65]
	s_waitcnt vmcnt(8)
	v_mov_b32_e32 v64, v206
	v_mov_b32_e32 v65, v207
	v_mov_b32_e32 v66, v208
	v_mov_b32_e32 v67, v209
	s_nop 0
	v_mov_b32_e32 v68, v210
	v_mov_b32_e32 v69, v211
	v_mov_b32_e32 v70, v212
	v_mov_b32_e32 v71, v213
	s_nop 0
	v_mov_b32_e32 v72, v214
	v_mov_b32_e32 v73, v215
	v_mov_b32_e32 v74, v216
	v_mov_b32_e32 v75, v217
	s_nop 0
	v_mov_b32_e32 v76, v218
	v_mov_b32_e32 v77, v219
	v_mov_b32_e32 v78, v220
	v_mov_b32_e32 v79, v221
	v_lshlrev_b64 v[80:81], 12, v[100:101]
	v_lshl_add_u64 v[84:85], v[148:149], 0, v[80:81]
	v_mov_b32_e32 v80, v222
	v_mov_b32_e32 v81, v223
	v_mov_b32_e32 v82, v224
	v_mov_b32_e32 v83, v225
	s_nop 0
	v_mov_b32_e32 v84, v226
	v_mov_b32_e32 v85, v227
	v_mov_b32_e32 v86, v228
	v_mov_b32_e32 v87, v229
	v_lshlrev_b64 v[88:89], 12, v[102:103]
	v_lshl_add_u64 v[92:93], v[148:149], 0, v[88:89]
	v_mov_b32_e32 v88, v230
	v_mov_b32_e32 v89, v231
	v_mov_b32_e32 v90, v232
	v_mov_b32_e32 v91, v233
	s_nop 0
	v_mov_b32_e32 v92, v234
	v_mov_b32_e32 v93, v235
	v_mov_b32_e32 v94, v236
	v_mov_b32_e32 v95, v237
	v_lshlrev_b64 v[96:97], 11, v[96:97]
	v_lshl_add_u64 v[96:97], s[42:43], 0, v[96:97]
	v_lshl_add_u64 v[96:97], v[96:97], 0, v[144:145]
	s_nop 0
	v_lshlrev_b32_e32 v104, 16, v64
	v_and_b32_e32 v64, 0xffff0000, v64
	v_mul_f32_e32 v61, v61, v64
	v_lshlrev_b32_e32 v64, 16, v65
	v_mul_f32_e32 v62, v62, v64
	v_and_b32_e32 v64, 0xffff0000, v65
	v_mul_f32_e32 v63, v63, v64
	v_lshlrev_b32_e32 v64, 16, v66
	v_mul_f32_e32 v64, v56, v64
	v_and_b32_e32 v56, 0xffff0000, v66
	v_mul_f32_e32 v65, v57, v56
	v_lshlrev_b32_e32 v56, 16, v67
	v_mul_f32_e32 v66, v58, v56
	v_and_b32_e32 v56, 0xffff0000, v67
	v_mul_f32_e32 v60, v60, v104
	v_mul_f32_e32 v59, v59, v56
	v_cvt_pk_bf16_f32 v56, v60, v61
	v_cvt_pk_bf16_f32 v57, v62, v63
	v_cvt_pk_bf16_f32 v58, v64, v65
	v_cvt_pk_bf16_f32 v59, v66, v59
	global_store_dwordx4 v[96:97], v[56:59], off
	s_nop 0
	s_nop 0
	v_lshlrev_b32_e32 v56, 16, v68
	v_mul_f32_e32 v52, v52, v56
	v_and_b32_e32 v56, 0xffff0000, v68
	v_mul_f32_e32 v53, v53, v56
	v_lshlrev_b32_e32 v56, 16, v69
	v_mul_f32_e32 v54, v54, v56
	v_and_b32_e32 v56, 0xffff0000, v69
	v_mul_f32_e32 v55, v55, v56
	v_lshlrev_b32_e32 v56, 16, v70
	v_mul_f32_e32 v56, v44, v56
	v_and_b32_e32 v44, 0xffff0000, v70
	v_mul_f32_e32 v57, v45, v44
	v_lshlrev_b32_e32 v44, 16, v71
	v_mul_f32_e32 v58, v46, v44
	v_and_b32_e32 v44, 0xffff0000, v71
	v_mul_f32_e32 v47, v47, v44
	v_cvt_pk_bf16_f32 v44, v52, v53
	v_cvt_pk_bf16_f32 v45, v54, v55
	v_cvt_pk_bf16_f32 v46, v56, v57
	v_cvt_pk_bf16_f32 v47, v58, v47
	global_store_dwordx4 v[96:97], v[44:47], off offset:256
	s_nop 0
	s_nop 0
	v_lshlrev_b32_e32 v46, 16, v72
	v_mul_f32_e32 v46, v48, v46
	v_lshlrev_b32_e32 v48, 16, v73
	v_and_b32_e32 v47, 0xffff0000, v72
	v_mul_f32_e32 v48, v50, v48
	v_lshlrev_b32_e32 v50, 16, v74
	v_mul_f32_e32 v47, v49, v47
	v_and_b32_e32 v49, 0xffff0000, v73
	v_mul_f32_e32 v50, v40, v50
	v_and_b32_e32 v40, 0xffff0000, v74
	v_lshlrev_b64 v[44:45], 11, v[98:99]
	v_mul_f32_e32 v49, v51, v49
	v_mul_f32_e32 v51, v41, v40
	v_lshlrev_b32_e32 v40, 16, v75
	v_lshl_add_u64 v[44:45], s[42:43], 0, v[44:45]
	v_mul_f32_e32 v52, v42, v40
	v_and_b32_e32 v40, 0xffff0000, v75
	v_lshl_add_u64 v[44:45], v[44:45], 0, v[144:145]
	v_mul_f32_e32 v43, v43, v40
	v_cvt_pk_bf16_f32 v40, v46, v47
	v_cvt_pk_bf16_f32 v41, v48, v49
	v_cvt_pk_bf16_f32 v42, v50, v51
	v_cvt_pk_bf16_f32 v43, v52, v43
	global_store_dwordx4 v[44:45], v[40:43], off
	s_nop 0
	s_nop 0
	v_lshlrev_b32_e32 v40, 16, v76
	v_mul_f32_e32 v36, v36, v40
	v_and_b32_e32 v40, 0xffff0000, v76
	v_mul_f32_e32 v37, v37, v40
	v_lshlrev_b32_e32 v40, 16, v77
	v_mul_f32_e32 v38, v38, v40
	v_and_b32_e32 v40, 0xffff0000, v77
	v_mul_f32_e32 v39, v39, v40
	v_lshlrev_b32_e32 v40, 16, v78
	v_mul_f32_e32 v40, v28, v40
	v_and_b32_e32 v28, 0xffff0000, v78
	v_mul_f32_e32 v41, v29, v28
	v_lshlrev_b32_e32 v28, 16, v79
	v_mul_f32_e32 v42, v30, v28
	v_and_b32_e32 v28, 0xffff0000, v79
	v_mul_f32_e32 v31, v31, v28
	v_cvt_pk_bf16_f32 v28, v36, v37
	v_cvt_pk_bf16_f32 v29, v38, v39
	v_cvt_pk_bf16_f32 v30, v40, v41
	v_cvt_pk_bf16_f32 v31, v42, v31
	global_store_dwordx4 v[44:45], v[28:31], off offset:256
	s_nop 0
	s_nop 0
	v_lshlrev_b32_e32 v30, 16, v80
	v_mul_f32_e32 v30, v32, v30
	v_lshlrev_b32_e32 v32, 16, v81
	v_and_b32_e32 v31, 0xffff0000, v80
	v_mul_f32_e32 v32, v34, v32
	v_lshlrev_b32_e32 v34, 16, v82
	v_mul_f32_e32 v31, v33, v31
	v_and_b32_e32 v33, 0xffff0000, v81
	v_mul_f32_e32 v34, v24, v34
	v_and_b32_e32 v24, 0xffff0000, v82
	v_lshlrev_b64 v[28:29], 11, v[100:101]
	v_mul_f32_e32 v33, v35, v33
	v_mul_f32_e32 v35, v25, v24
	v_lshlrev_b32_e32 v24, 16, v83
	v_lshl_add_u64 v[28:29], s[42:43], 0, v[28:29]
	v_mul_f32_e32 v36, v26, v24
	v_and_b32_e32 v24, 0xffff0000, v83
	v_lshl_add_u64 v[28:29], v[28:29], 0, v[144:145]
	v_mul_f32_e32 v27, v27, v24
	v_cvt_pk_bf16_f32 v24, v30, v31
	v_cvt_pk_bf16_f32 v25, v32, v33
	v_cvt_pk_bf16_f32 v26, v34, v35
	v_cvt_pk_bf16_f32 v27, v36, v27
	global_store_dwordx4 v[28:29], v[24:27], off
	s_nop 0
	s_nop 0
	v_lshlrev_b32_e32 v24, 16, v84
	v_mul_f32_e32 v20, v20, v24
	v_and_b32_e32 v24, 0xffff0000, v84
	v_mul_f32_e32 v21, v21, v24
	v_lshlrev_b32_e32 v24, 16, v85
	v_mul_f32_e32 v22, v22, v24
	v_and_b32_e32 v24, 0xffff0000, v85
	v_mul_f32_e32 v23, v23, v24
	v_lshlrev_b32_e32 v24, 16, v86
	v_mul_f32_e32 v24, v12, v24
	v_and_b32_e32 v12, 0xffff0000, v86
	v_mul_f32_e32 v25, v13, v12
	v_lshlrev_b32_e32 v12, 16, v87
	v_mul_f32_e32 v26, v14, v12
	v_and_b32_e32 v12, 0xffff0000, v87
	v_mul_f32_e32 v15, v15, v12
	v_cvt_pk_bf16_f32 v12, v20, v21
	v_cvt_pk_bf16_f32 v13, v22, v23
	v_cvt_pk_bf16_f32 v14, v24, v25
	v_cvt_pk_bf16_f32 v15, v26, v15
	global_store_dwordx4 v[28:29], v[12:15], off offset:256
	s_nop 0
	s_nop 0
	v_lshlrev_b32_e32 v14, 16, v88
	v_mul_f32_e32 v14, v16, v14
	v_lshlrev_b32_e32 v16, 16, v89
	v_and_b32_e32 v15, 0xffff0000, v88
	v_mul_f32_e32 v16, v18, v16
	v_lshlrev_b32_e32 v18, 16, v90
	v_mul_f32_e32 v15, v17, v15
	v_and_b32_e32 v17, 0xffff0000, v89
	v_mul_f32_e32 v18, v8, v18
	v_and_b32_e32 v8, 0xffff0000, v90
	v_lshlrev_b64 v[12:13], 11, v[102:103]
	v_mul_f32_e32 v17, v19, v17
	v_mul_f32_e32 v19, v9, v8
	v_lshlrev_b32_e32 v8, 16, v91
	v_lshl_add_u64 v[12:13], s[42:43], 0, v[12:13]
	v_mul_f32_e32 v20, v10, v8
	v_and_b32_e32 v8, 0xffff0000, v91
	v_lshl_add_u64 v[12:13], v[12:13], 0, v[144:145]
	v_mul_f32_e32 v11, v11, v8
	v_cvt_pk_bf16_f32 v8, v14, v15
	v_cvt_pk_bf16_f32 v9, v16, v17
	v_cvt_pk_bf16_f32 v10, v18, v19
	v_cvt_pk_bf16_f32 v11, v20, v11
	global_store_dwordx4 v[12:13], v[8:11], off
	s_nop 0
	s_nop 0
	v_lshlrev_b32_e32 v8, 16, v92
	v_mul_f32_e32 v4, v4, v8
	v_and_b32_e32 v8, 0xffff0000, v92
	v_mul_f32_e32 v5, v5, v8
	v_lshlrev_b32_e32 v8, 16, v93
	v_mul_f32_e32 v6, v6, v8
	v_and_b32_e32 v8, 0xffff0000, v93
	v_mul_f32_e32 v7, v7, v8
	v_lshlrev_b32_e32 v8, 16, v94
	v_mul_f32_e32 v8, v0, v8
	v_and_b32_e32 v0, 0xffff0000, v94
	v_mul_f32_e32 v9, v1, v0
	v_lshlrev_b32_e32 v0, 16, v95
	v_mul_f32_e32 v10, v2, v0
	v_and_b32_e32 v0, 0xffff0000, v95
	v_mul_f32_e32 v3, v3, v0
	v_cvt_pk_bf16_f32 v0, v4, v5
	v_cvt_pk_bf16_f32 v1, v6, v7
	v_cvt_pk_bf16_f32 v2, v8, v9
	v_cvt_pk_bf16_f32 v3, v10, v3
	global_store_dwordx4 v[12:13], v[0:3], off offset:256
	s_mov_b32 s99, 1
	s_cbranch_vccnz .LBB0_3130
	s_andn2_b64 vcc, exec, s[0:1]
	s_cbranch_vccnz .LBB0_3129
	s_barrier
	s_branch .LBB0_3129
